# phase 0: modulation GEMV loop keeps 32 row loads in flight (was one load per wait); the four big weight matrices converted by a streaming register-transpose pass with chunks taken from per-slot counte
# speedup vs baseline: 1.0044x; 1.0044x over previous
.LBB0_1248:
	s_cmpk_gt_u32 s70, 0x11f
	s_cbranch_scc0 .Lcv_keep
	s_cmpk_gt_u32 s70, 0x15ff
	s_cbranch_scc0 .LBB0_1247

.LBB0_1356:
	s_mov_b64 s[40:41], 0x9000
	v_mov_b32_e32 v18, v16
	v_mov_b32_e32 v19, v17
	global_load_dwordx4 v[44:47], v[18:19], off
	v_lshl_add_u64 v[18:19], v[18:19], 0, s[40:41]
	global_load_dwordx4 v[48:51], v[18:19], off
	v_lshl_add_u64 v[18:19], v[18:19], 0, s[40:41]
	global_load_dwordx4 v[52:55], v[18:19], off
	v_lshl_add_u64 v[18:19], v[18:19], 0, s[40:41]
	global_load_dwordx4 v[56:59], v[18:19], off
	v_lshl_add_u64 v[18:19], v[18:19], 0, s[40:41]
	global_load_dwordx4 v[60:63], v[18:19], off
	v_lshl_add_u64 v[18:19], v[18:19], 0, s[40:41]
	global_load_dwordx4 v[64:67], v[18:19], off
	v_lshl_add_u64 v[18:19], v[18:19], 0, s[40:41]
	global_load_dwordx4 v[68:71], v[18:19], off
	v_lshl_add_u64 v[18:19], v[18:19], 0, s[40:41]
	global_load_dwordx4 v[72:75], v[18:19], off
	v_lshl_add_u64 v[18:19], v[18:19], 0, s[40:41]
	global_load_dwordx4 v[76:79], v[18:19], off
	v_lshl_add_u64 v[18:19], v[18:19], 0, s[40:41]
	global_load_dwordx4 v[80:83], v[18:19], off
	v_lshl_add_u64 v[18:19], v[18:19], 0, s[40:41]
	global_load_dwordx4 v[84:87], v[18:19], off
	v_lshl_add_u64 v[18:19], v[18:19], 0, s[40:41]
	global_load_dwordx4 v[88:91], v[18:19], off
	v_lshl_add_u64 v[18:19], v[18:19], 0, s[40:41]
	global_load_dwordx4 v[92:95], v[18:19], off
	v_lshl_add_u64 v[18:19], v[18:19], 0, s[40:41]
	global_load_dwordx4 v[96:99], v[18:19], off
	v_lshl_add_u64 v[18:19], v[18:19], 0, s[40:41]
	global_load_dwordx4 v[100:103], v[18:19], off
	v_lshl_add_u64 v[18:19], v[18:19], 0, s[40:41]
	global_load_dwordx4 v[104:107], v[18:19], off
	v_lshl_add_u64 v[18:19], v[18:19], 0, s[40:41]
	global_load_dwordx4 v[108:111], v[18:19], off
	v_lshl_add_u64 v[18:19], v[18:19], 0, s[40:41]
	global_load_dwordx4 v[112:115], v[18:19], off
	v_lshl_add_u64 v[18:19], v[18:19], 0, s[40:41]
	global_load_dwordx4 v[116:119], v[18:19], off
	v_lshl_add_u64 v[18:19], v[18:19], 0, s[40:41]
	global_load_dwordx4 v[120:123], v[18:19], off
	v_lshl_add_u64 v[18:19], v[18:19], 0, s[40:41]
	global_load_dwordx4 v[124:127], v[18:19], off
	v_lshl_add_u64 v[18:19], v[18:19], 0, s[40:41]
	global_load_dwordx4 v[136:139], v[18:19], off
	v_lshl_add_u64 v[18:19], v[18:19], 0, s[40:41]
	global_load_dwordx4 v[140:143], v[18:19], off
	v_lshl_add_u64 v[18:19], v[18:19], 0, s[40:41]
	global_load_dwordx4 v[144:147], v[18:19], off
	v_lshl_add_u64 v[18:19], v[18:19], 0, s[40:41]
	global_load_dwordx4 v[148:151], v[18:19], off
	v_lshl_add_u64 v[18:19], v[18:19], 0, s[40:41]
	global_load_dwordx4 v[152:155], v[18:19], off
	v_lshl_add_u64 v[18:19], v[18:19], 0, s[40:41]
	global_load_dwordx4 v[156:159], v[18:19], off
	v_lshl_add_u64 v[18:19], v[18:19], 0, s[40:41]
	global_load_dwordx4 v[160:163], v[18:19], off
	v_lshl_add_u64 v[18:19], v[18:19], 0, s[40:41]
	global_load_dwordx4 v[164:167], v[18:19], off
	v_lshl_add_u64 v[18:19], v[18:19], 0, s[40:41]
	global_load_dwordx4 v[202:205], v[18:19], off
	v_lshl_add_u64 v[18:19], v[18:19], 0, s[40:41]
	global_load_dwordx4 v[206:209], v[18:19], off
	v_lshl_add_u64 v[18:19], v[18:19], 0, s[40:41]
	global_load_dwordx4 v[210:213], v[18:19], off
	v_lshl_add_u64 v[18:19], v[18:19], 0, s[40:41]
	ds_read_b128 v[24:27], v23
	ds_read_b128 v[28:31], v23 offset:4096
	ds_read_b128 v[32:35], v23 offset:8192
	ds_read_b128 v[36:39], v23 offset:16
	ds_read_b128 v[40:43], v23 offset:4112
	ds_read_b128 v[0:3], v23 offset:8208
	s_waitcnt lgkmcnt(3)
	s_waitcnt vmcnt(31)
	v_pk_fma_f32 v[4:5], v[44:45], v[24:25], v[4:5] op_sel_hi:[1,0,1]
	v_pk_fma_f32 v[6:7], v[46:47], v[24:25], v[6:7] op_sel_hi:[1,0,1]
	v_pk_fma_f32 v[12:13], v[44:45], v[28:29], v[12:13] op_sel_hi:[1,0,1]
	v_pk_fma_f32 v[14:15], v[46:47], v[28:29], v[14:15] op_sel_hi:[1,0,1]
	v_pk_fma_f32 v[8:9], v[44:45], v[32:33], v[8:9] op_sel_hi:[1,0,1]
	v_pk_fma_f32 v[10:11], v[46:47], v[32:33], v[10:11] op_sel_hi:[1,0,1]
	global_load_dwordx4 v[44:47], v[18:19], off
	v_lshl_add_u64 v[18:19], v[18:19], 0, s[40:41]
	s_waitcnt vmcnt(31)
	v_pk_fma_f32 v[4:5], v[48:49], v[24:25], v[4:5] op_sel:[0,1,0]
	v_pk_fma_f32 v[6:7], v[50:51], v[24:25], v[6:7] op_sel:[0,1,0]
	v_pk_fma_f32 v[12:13], v[48:49], v[28:29], v[12:13] op_sel:[0,1,0]
	v_pk_fma_f32 v[14:15], v[50:51], v[28:29], v[14:15] op_sel:[0,1,0]
	v_pk_fma_f32 v[8:9], v[48:49], v[32:33], v[8:9] op_sel:[0,1,0]
	v_pk_fma_f32 v[10:11], v[50:51], v[32:33], v[10:11] op_sel:[0,1,0]
	global_load_dwordx4 v[48:51], v[18:19], off
	v_lshl_add_u64 v[18:19], v[18:19], 0, s[40:41]
	s_waitcnt vmcnt(31)
	v_pk_fma_f32 v[4:5], v[52:53], v[26:27], v[4:5] op_sel_hi:[1,0,1]
	v_pk_fma_f32 v[6:7], v[54:55], v[26:27], v[6:7] op_sel_hi:[1,0,1]
	v_pk_fma_f32 v[12:13], v[52:53], v[30:31], v[12:13] op_sel_hi:[1,0,1]
	v_pk_fma_f32 v[14:15], v[54:55], v[30:31], v[14:15] op_sel_hi:[1,0,1]
	v_pk_fma_f32 v[8:9], v[52:53], v[34:35], v[8:9] op_sel_hi:[1,0,1]
	v_pk_fma_f32 v[10:11], v[54:55], v[34:35], v[10:11] op_sel_hi:[1,0,1]
	global_load_dwordx4 v[52:55], v[18:19], off
	v_lshl_add_u64 v[18:19], v[18:19], 0, s[40:41]
	s_waitcnt vmcnt(31)
	v_pk_fma_f32 v[4:5], v[56:57], v[26:27], v[4:5] op_sel:[0,1,0]
	v_pk_fma_f32 v[6:7], v[58:59], v[26:27], v[6:7] op_sel:[0,1,0]
	v_pk_fma_f32 v[12:13], v[56:57], v[30:31], v[12:13] op_sel:[0,1,0]
	v_pk_fma_f32 v[14:15], v[58:59], v[30:31], v[14:15] op_sel:[0,1,0]
	v_pk_fma_f32 v[8:9], v[56:57], v[34:35], v[8:9] op_sel:[0,1,0]
	v_pk_fma_f32 v[10:11], v[58:59], v[34:35], v[10:11] op_sel:[0,1,0]
	global_load_dwordx4 v[56:59], v[18:19], off
	v_lshl_add_u64 v[18:19], v[18:19], 0, s[40:41]
	ds_read_b128 v[24:27], v23 offset:32
	ds_read_b128 v[28:31], v23 offset:4128
	ds_read_b128 v[32:35], v23 offset:8224
	s_waitcnt lgkmcnt(3)
	s_waitcnt vmcnt(31)
	v_pk_fma_f32 v[4:5], v[60:61], v[36:37], v[4:5] op_sel_hi:[1,0,1]
	v_pk_fma_f32 v[6:7], v[62:63], v[36:37], v[6:7] op_sel_hi:[1,0,1]
	v_pk_fma_f32 v[12:13], v[60:61], v[40:41], v[12:13] op_sel_hi:[1,0,1]
	v_pk_fma_f32 v[14:15], v[62:63], v[40:41], v[14:15] op_sel_hi:[1,0,1]
	v_pk_fma_f32 v[8:9], v[60:61], v[0:1], v[8:9] op_sel_hi:[1,0,1]
	v_pk_fma_f32 v[10:11], v[62:63], v[0:1], v[10:11] op_sel_hi:[1,0,1]
	global_load_dwordx4 v[60:63], v[18:19], off
	v_lshl_add_u64 v[18:19], v[18:19], 0, s[40:41]
	s_waitcnt vmcnt(31)
	v_pk_fma_f32 v[4:5], v[64:65], v[36:37], v[4:5] op_sel:[0,1,0]
	v_pk_fma_f32 v[6:7], v[66:67], v[36:37], v[6:7] op_sel:[0,1,0]
	v_pk_fma_f32 v[12:13], v[64:65], v[40:41], v[12:13] op_sel:[0,1,0]
	v_pk_fma_f32 v[14:15], v[66:67], v[40:41], v[14:15] op_sel:[0,1,0]
	v_pk_fma_f32 v[8:9], v[64:65], v[0:1], v[8:9] op_sel:[0,1,0]
	v_pk_fma_f32 v[10:11], v[66:67], v[0:1], v[10:11] op_sel:[0,1,0]
	global_load_dwordx4 v[64:67], v[18:19], off
	v_lshl_add_u64 v[18:19], v[18:19], 0, s[40:41]
	s_waitcnt vmcnt(31)
	v_pk_fma_f32 v[4:5], v[68:69], v[38:39], v[4:5] op_sel_hi:[1,0,1]
	v_pk_fma_f32 v[6:7], v[70:71], v[38:39], v[6:7] op_sel_hi:[1,0,1]
	v_pk_fma_f32 v[12:13], v[68:69], v[42:43], v[12:13] op_sel_hi:[1,0,1]
	v_pk_fma_f32 v[14:15], v[70:71], v[42:43], v[14:15] op_sel_hi:[1,0,1]
	v_pk_fma_f32 v[8:9], v[68:69], v[2:3], v[8:9] op_sel_hi:[1,0,1]
	v_pk_fma_f32 v[10:11], v[70:71], v[2:3], v[10:11] op_sel_hi:[1,0,1]
	global_load_dwordx4 v[68:71], v[18:19], off
	v_lshl_add_u64 v[18:19], v[18:19], 0, s[40:41]
	s_waitcnt vmcnt(31)
	v_pk_fma_f32 v[4:5], v[72:73], v[38:39], v[4:5] op_sel:[0,1,0]
	v_pk_fma_f32 v[6:7], v[74:75], v[38:39], v[6:7] op_sel:[0,1,0]
	v_pk_fma_f32 v[12:13], v[72:73], v[42:43], v[12:13] op_sel:[0,1,0]
	v_pk_fma_f32 v[14:15], v[74:75], v[42:43], v[14:15] op_sel:[0,1,0]
	v_pk_fma_f32 v[8:9], v[72:73], v[2:3], v[8:9] op_sel:[0,1,0]
	v_pk_fma_f32 v[10:11], v[74:75], v[2:3], v[10:11] op_sel:[0,1,0]
	global_load_dwordx4 v[72:75], v[18:19], off
	v_lshl_add_u64 v[18:19], v[18:19], 0, s[40:41]
	ds_read_b128 v[36:39], v23 offset:48
	ds_read_b128 v[40:43], v23 offset:4144
	ds_read_b128 v[0:3], v23 offset:8240
	s_waitcnt lgkmcnt(3)
	s_waitcnt vmcnt(31)
	v_pk_fma_f32 v[4:5], v[76:77], v[24:25], v[4:5] op_sel_hi:[1,0,1]
	v_pk_fma_f32 v[6:7], v[78:79], v[24:25], v[6:7] op_sel_hi:[1,0,1]
	v_pk_fma_f32 v[12:13], v[76:77], v[28:29], v[12:13] op_sel_hi:[1,0,1]
	v_pk_fma_f32 v[14:15], v[78:79], v[28:29], v[14:15] op_sel_hi:[1,0,1]
	v_pk_fma_f32 v[8:9], v[76:77], v[32:33], v[8:9] op_sel_hi:[1,0,1]
	v_pk_fma_f32 v[10:11], v[78:79], v[32:33], v[10:11] op_sel_hi:[1,0,1]
	global_load_dwordx4 v[76:79], v[18:19], off
	v_lshl_add_u64 v[18:19], v[18:19], 0, s[40:41]
	s_waitcnt vmcnt(31)
	v_pk_fma_f32 v[4:5], v[80:81], v[24:25], v[4:5] op_sel:[0,1,0]
	v_pk_fma_f32 v[6:7], v[82:83], v[24:25], v[6:7] op_sel:[0,1,0]
	v_pk_fma_f32 v[12:13], v[80:81], v[28:29], v[12:13] op_sel:[0,1,0]
	v_pk_fma_f32 v[14:15], v[82:83], v[28:29], v[14:15] op_sel:[0,1,0]
	v_pk_fma_f32 v[8:9], v[80:81], v[32:33], v[8:9] op_sel:[0,1,0]
	v_pk_fma_f32 v[10:11], v[82:83], v[32:33], v[10:11] op_sel:[0,1,0]
	global_load_dwordx4 v[80:83], v[18:19], off
	v_lshl_add_u64 v[18:19], v[18:19], 0, s[40:41]
	s_waitcnt vmcnt(31)
	v_pk_fma_f32 v[4:5], v[84:85], v[26:27], v[4:5] op_sel_hi:[1,0,1]
	v_pk_fma_f32 v[6:7], v[86:87], v[26:27], v[6:7] op_sel_hi:[1,0,1]
	v_pk_fma_f32 v[12:13], v[84:85], v[30:31], v[12:13] op_sel_hi:[1,0,1]
	v_pk_fma_f32 v[14:15], v[86:87], v[30:31], v[14:15] op_sel_hi:[1,0,1]
	v_pk_fma_f32 v[8:9], v[84:85], v[34:35], v[8:9] op_sel_hi:[1,0,1]
	v_pk_fma_f32 v[10:11], v[86:87], v[34:35], v[10:11] op_sel_hi:[1,0,1]
	global_load_dwordx4 v[84:87], v[18:19], off
	v_lshl_add_u64 v[18:19], v[18:19], 0, s[40:41]
	s_waitcnt vmcnt(31)
	v_pk_fma_f32 v[4:5], v[88:89], v[26:27], v[4:5] op_sel:[0,1,0]
	v_pk_fma_f32 v[6:7], v[90:91], v[26:27], v[6:7] op_sel:[0,1,0]
	v_pk_fma_f32 v[12:13], v[88:89], v[30:31], v[12:13] op_sel:[0,1,0]
	v_pk_fma_f32 v[14:15], v[90:91], v[30:31], v[14:15] op_sel:[0,1,0]
	v_pk_fma_f32 v[8:9], v[88:89], v[34:35], v[8:9] op_sel:[0,1,0]
	v_pk_fma_f32 v[10:11], v[90:91], v[34:35], v[10:11] op_sel:[0,1,0]
	global_load_dwordx4 v[88:91], v[18:19], off
	v_lshl_add_u64 v[18:19], v[18:19], 0, s[40:41]
	ds_read_b128 v[24:27], v23 offset:64
	ds_read_b128 v[28:31], v23 offset:4160
	ds_read_b128 v[32:35], v23 offset:8256
	s_waitcnt lgkmcnt(3)
	s_waitcnt vmcnt(31)
	v_pk_fma_f32 v[4:5], v[92:93], v[36:37], v[4:5] op_sel_hi:[1,0,1]
	v_pk_fma_f32 v[6:7], v[94:95], v[36:37], v[6:7] op_sel_hi:[1,0,1]
	v_pk_fma_f32 v[12:13], v[92:93], v[40:41], v[12:13] op_sel_hi:[1,0,1]
	v_pk_fma_f32 v[14:15], v[94:95], v[40:41], v[14:15] op_sel_hi:[1,0,1]
	v_pk_fma_f32 v[8:9], v[92:93], v[0:1], v[8:9] op_sel_hi:[1,0,1]
	v_pk_fma_f32 v[10:11], v[94:95], v[0:1], v[10:11] op_sel_hi:[1,0,1]
	global_load_dwordx4 v[92:95], v[18:19], off
	v_lshl_add_u64 v[18:19], v[18:19], 0, s[40:41]
	s_waitcnt vmcnt(31)
	v_pk_fma_f32 v[4:5], v[96:97], v[36:37], v[4:5] op_sel:[0,1,0]
	v_pk_fma_f32 v[6:7], v[98:99], v[36:37], v[6:7] op_sel:[0,1,0]
	v_pk_fma_f32 v[12:13], v[96:97], v[40:41], v[12:13] op_sel:[0,1,0]
	v_pk_fma_f32 v[14:15], v[98:99], v[40:41], v[14:15] op_sel:[0,1,0]
	v_pk_fma_f32 v[8:9], v[96:97], v[0:1], v[8:9] op_sel:[0,1,0]
	v_pk_fma_f32 v[10:11], v[98:99], v[0:1], v[10:11] op_sel:[0,1,0]
	global_load_dwordx4 v[96:99], v[18:19], off
	v_lshl_add_u64 v[18:19], v[18:19], 0, s[40:41]
	s_waitcnt vmcnt(31)
	v_pk_fma_f32 v[4:5], v[100:101], v[38:39], v[4:5] op_sel_hi:[1,0,1]
	v_pk_fma_f32 v[6:7], v[102:103], v[38:39], v[6:7] op_sel_hi:[1,0,1]
	v_pk_fma_f32 v[12:13], v[100:101], v[42:43], v[12:13] op_sel_hi:[1,0,1]
	v_pk_fma_f32 v[14:15], v[102:103], v[42:43], v[14:15] op_sel_hi:[1,0,1]
	v_pk_fma_f32 v[8:9], v[100:101], v[2:3], v[8:9] op_sel_hi:[1,0,1]
	v_pk_fma_f32 v[10:11], v[102:103], v[2:3], v[10:11] op_sel_hi:[1,0,1]
	global_load_dwordx4 v[100:103], v[18:19], off
	v_lshl_add_u64 v[18:19], v[18:19], 0, s[40:41]
	s_waitcnt vmcnt(31)
	v_pk_fma_f32 v[4:5], v[104:105], v[38:39], v[4:5] op_sel:[0,1,0]
	v_pk_fma_f32 v[6:7], v[106:107], v[38:39], v[6:7] op_sel:[0,1,0]
	v_pk_fma_f32 v[12:13], v[104:105], v[42:43], v[12:13] op_sel:[0,1,0]
	v_pk_fma_f32 v[14:15], v[106:107], v[42:43], v[14:15] op_sel:[0,1,0]
	v_pk_fma_f32 v[8:9], v[104:105], v[2:3], v[8:9] op_sel:[0,1,0]
	v_pk_fma_f32 v[10:11], v[106:107], v[2:3], v[10:11] op_sel:[0,1,0]
	global_load_dwordx4 v[104:107], v[18:19], off
	v_lshl_add_u64 v[18:19], v[18:19], 0, s[40:41]
	ds_read_b128 v[36:39], v23 offset:80
	ds_read_b128 v[40:43], v23 offset:4176
	ds_read_b128 v[0:3], v23 offset:8272
	s_waitcnt lgkmcnt(3)
	s_waitcnt vmcnt(31)
	v_pk_fma_f32 v[4:5], v[108:109], v[24:25], v[4:5] op_sel_hi:[1,0,1]
	v_pk_fma_f32 v[6:7], v[110:111], v[24:25], v[6:7] op_sel_hi:[1,0,1]
	v_pk_fma_f32 v[12:13], v[108:109], v[28:29], v[12:13] op_sel_hi:[1,0,1]
	v_pk_fma_f32 v[14:15], v[110:111], v[28:29], v[14:15] op_sel_hi:[1,0,1]
	v_pk_fma_f32 v[8:9], v[108:109], v[32:33], v[8:9] op_sel_hi:[1,0,1]
	v_pk_fma_f32 v[10:11], v[110:111], v[32:33], v[10:11] op_sel_hi:[1,0,1]
	global_load_dwordx4 v[108:111], v[18:19], off
	v_lshl_add_u64 v[18:19], v[18:19], 0, s[40:41]
	s_waitcnt vmcnt(31)
	v_pk_fma_f32 v[4:5], v[112:113], v[24:25], v[4:5] op_sel:[0,1,0]
	v_pk_fma_f32 v[6:7], v[114:115], v[24:25], v[6:7] op_sel:[0,1,0]
	v_pk_fma_f32 v[12:13], v[112:113], v[28:29], v[12:13] op_sel:[0,1,0]
	v_pk_fma_f32 v[14:15], v[114:115], v[28:29], v[14:15] op_sel:[0,1,0]
	v_pk_fma_f32 v[8:9], v[112:113], v[32:33], v[8:9] op_sel:[0,1,0]
	v_pk_fma_f32 v[10:11], v[114:115], v[32:33], v[10:11] op_sel:[0,1,0]
	global_load_dwordx4 v[112:115], v[18:19], off
	v_lshl_add_u64 v[18:19], v[18:19], 0, s[40:41]
	s_waitcnt vmcnt(31)
	v_pk_fma_f32 v[4:5], v[116:117], v[26:27], v[4:5] op_sel_hi:[1,0,1]
	v_pk_fma_f32 v[6:7], v[118:119], v[26:27], v[6:7] op_sel_hi:[1,0,1]
	v_pk_fma_f32 v[12:13], v[116:117], v[30:31], v[12:13] op_sel_hi:[1,0,1]
	v_pk_fma_f32 v[14:15], v[118:119], v[30:31], v[14:15] op_sel_hi:[1,0,1]
	v_pk_fma_f32 v[8:9], v[116:117], v[34:35], v[8:9] op_sel_hi:[1,0,1]
	v_pk_fma_f32 v[10:11], v[118:119], v[34:35], v[10:11] op_sel_hi:[1,0,1]
	global_load_dwordx4 v[116:119], v[18:19], off
	v_lshl_add_u64 v[18:19], v[18:19], 0, s[40:41]
	s_waitcnt vmcnt(31)
	v_pk_fma_f32 v[4:5], v[120:121], v[26:27], v[4:5] op_sel:[0,1,0]
	v_pk_fma_f32 v[6:7], v[122:123], v[26:27], v[6:7] op_sel:[0,1,0]
	v_pk_fma_f32 v[12:13], v[120:121], v[30:31], v[12:13] op_sel:[0,1,0]
	v_pk_fma_f32 v[14:15], v[122:123], v[30:31], v[14:15] op_sel:[0,1,0]
	v_pk_fma_f32 v[8:9], v[120:121], v[34:35], v[8:9] op_sel:[0,1,0]
	v_pk_fma_f32 v[10:11], v[122:123], v[34:35], v[10:11] op_sel:[0,1,0]
	global_load_dwordx4 v[120:123], v[18:19], off
	v_lshl_add_u64 v[18:19], v[18:19], 0, s[40:41]
	ds_read_b128 v[24:27], v23 offset:96
	ds_read_b128 v[28:31], v23 offset:4192
	ds_read_b128 v[32:35], v23 offset:8288
	s_waitcnt lgkmcnt(3)
	s_waitcnt vmcnt(31)
	v_pk_fma_f32 v[4:5], v[124:125], v[36:37], v[4:5] op_sel_hi:[1,0,1]
	v_pk_fma_f32 v[6:7], v[126:127], v[36:37], v[6:7] op_sel_hi:[1,0,1]
	v_pk_fma_f32 v[12:13], v[124:125], v[40:41], v[12:13] op_sel_hi:[1,0,1]
	v_pk_fma_f32 v[14:15], v[126:127], v[40:41], v[14:15] op_sel_hi:[1,0,1]
	v_pk_fma_f32 v[8:9], v[124:125], v[0:1], v[8:9] op_sel_hi:[1,0,1]
	v_pk_fma_f32 v[10:11], v[126:127], v[0:1], v[10:11] op_sel_hi:[1,0,1]
	global_load_dwordx4 v[124:127], v[18:19], off
	v_lshl_add_u64 v[18:19], v[18:19], 0, s[40:41]
	s_waitcnt vmcnt(31)
	v_pk_fma_f32 v[4:5], v[136:137], v[36:37], v[4:5] op_sel:[0,1,0]
	v_pk_fma_f32 v[6:7], v[138:139], v[36:37], v[6:7] op_sel:[0,1,0]
	v_pk_fma_f32 v[12:13], v[136:137], v[40:41], v[12:13] op_sel:[0,1,0]
	v_pk_fma_f32 v[14:15], v[138:139], v[40:41], v[14:15] op_sel:[0,1,0]
	v_pk_fma_f32 v[8:9], v[136:137], v[0:1], v[8:9] op_sel:[0,1,0]
	v_pk_fma_f32 v[10:11], v[138:139], v[0:1], v[10:11] op_sel:[0,1,0]
	global_load_dwordx4 v[136:139], v[18:19], off
	v_lshl_add_u64 v[18:19], v[18:19], 0, s[40:41]
	s_waitcnt vmcnt(31)
	v_pk_fma_f32 v[4:5], v[140:141], v[38:39], v[4:5] op_sel_hi:[1,0,1]
	v_pk_fma_f32 v[6:7], v[142:143], v[38:39], v[6:7] op_sel_hi:[1,0,1]
	v_pk_fma_f32 v[12:13], v[140:141], v[42:43], v[12:13] op_sel_hi:[1,0,1]
	v_pk_fma_f32 v[14:15], v[142:143], v[42:43], v[14:15] op_sel_hi:[1,0,1]
	v_pk_fma_f32 v[8:9], v[140:141], v[2:3], v[8:9] op_sel_hi:[1,0,1]
	v_pk_fma_f32 v[10:11], v[142:143], v[2:3], v[10:11] op_sel_hi:[1,0,1]
	global_load_dwordx4 v[140:143], v[18:19], off
	v_lshl_add_u64 v[18:19], v[18:19], 0, s[40:41]
	s_waitcnt vmcnt(31)
	v_pk_fma_f32 v[4:5], v[144:145], v[38:39], v[4:5] op_sel:[0,1,0]
	v_pk_fma_f32 v[6:7], v[146:147], v[38:39], v[6:7] op_sel:[0,1,0]
	v_pk_fma_f32 v[12:13], v[144:145], v[42:43], v[12:13] op_sel:[0,1,0]
	v_pk_fma_f32 v[14:15], v[146:147], v[42:43], v[14:15] op_sel:[0,1,0]
	v_pk_fma_f32 v[8:9], v[144:145], v[2:3], v[8:9] op_sel:[0,1,0]
	v_pk_fma_f32 v[10:11], v[146:147], v[2:3], v[10:11] op_sel:[0,1,0]
	global_load_dwordx4 v[144:147], v[18:19], off
	v_lshl_add_u64 v[18:19], v[18:19], 0, s[40:41]
	ds_read_b128 v[36:39], v23 offset:112
	ds_read_b128 v[40:43], v23 offset:4208
	ds_read_b128 v[0:3], v23 offset:8304
	s_waitcnt lgkmcnt(3)
	s_waitcnt vmcnt(31)
	v_pk_fma_f32 v[4:5], v[148:149], v[24:25], v[4:5] op_sel_hi:[1,0,1]
	v_pk_fma_f32 v[6:7], v[150:151], v[24:25], v[6:7] op_sel_hi:[1,0,1]
	v_pk_fma_f32 v[12:13], v[148:149], v[28:29], v[12:13] op_sel_hi:[1,0,1]
	v_pk_fma_f32 v[14:15], v[150:151], v[28:29], v[14:15] op_sel_hi:[1,0,1]
	v_pk_fma_f32 v[8:9], v[148:149], v[32:33], v[8:9] op_sel_hi:[1,0,1]
	v_pk_fma_f32 v[10:11], v[150:151], v[32:33], v[10:11] op_sel_hi:[1,0,1]
	global_load_dwordx4 v[148:151], v[18:19], off
	v_lshl_add_u64 v[18:19], v[18:19], 0, s[40:41]
	s_waitcnt vmcnt(31)
	v_pk_fma_f32 v[4:5], v[152:153], v[24:25], v[4:5] op_sel:[0,1,0]
	v_pk_fma_f32 v[6:7], v[154:155], v[24:25], v[6:7] op_sel:[0,1,0]
	v_pk_fma_f32 v[12:13], v[152:153], v[28:29], v[12:13] op_sel:[0,1,0]
	v_pk_fma_f32 v[14:15], v[154:155], v[28:29], v[14:15] op_sel:[0,1,0]
	v_pk_fma_f32 v[8:9], v[152:153], v[32:33], v[8:9] op_sel:[0,1,0]
	v_pk_fma_f32 v[10:11], v[154:155], v[32:33], v[10:11] op_sel:[0,1,0]
	global_load_dwordx4 v[152:155], v[18:19], off
	v_lshl_add_u64 v[18:19], v[18:19], 0, s[40:41]
	s_waitcnt vmcnt(31)
	v_pk_fma_f32 v[4:5], v[156:157], v[26:27], v[4:5] op_sel_hi:[1,0,1]
	v_pk_fma_f32 v[6:7], v[158:159], v[26:27], v[6:7] op_sel_hi:[1,0,1]
	v_pk_fma_f32 v[12:13], v[156:157], v[30:31], v[12:13] op_sel_hi:[1,0,1]
	v_pk_fma_f32 v[14:15], v[158:159], v[30:31], v[14:15] op_sel_hi:[1,0,1]
	v_pk_fma_f32 v[8:9], v[156:157], v[34:35], v[8:9] op_sel_hi:[1,0,1]
	v_pk_fma_f32 v[10:11], v[158:159], v[34:35], v[10:11] op_sel_hi:[1,0,1]
	global_load_dwordx4 v[156:159], v[18:19], off
	v_lshl_add_u64 v[18:19], v[18:19], 0, s[40:41]
	s_waitcnt vmcnt(31)
	v_pk_fma_f32 v[4:5], v[160:161], v[26:27], v[4:5] op_sel:[0,1,0]
	v_pk_fma_f32 v[6:7], v[162:163], v[26:27], v[6:7] op_sel:[0,1,0]
	v_pk_fma_f32 v[12:13], v[160:161], v[30:31], v[12:13] op_sel:[0,1,0]
	v_pk_fma_f32 v[14:15], v[162:163], v[30:31], v[14:15] op_sel:[0,1,0]
	v_pk_fma_f32 v[8:9], v[160:161], v[34:35], v[8:9] op_sel:[0,1,0]
	v_pk_fma_f32 v[10:11], v[162:163], v[34:35], v[10:11] op_sel:[0,1,0]
	global_load_dwordx4 v[160:163], v[18:19], off
	v_lshl_add_u64 v[18:19], v[18:19], 0, s[40:41]
	ds_read_b128 v[24:27], v23 offset:128
	ds_read_b128 v[28:31], v23 offset:4224
	ds_read_b128 v[32:35], v23 offset:8320
	s_waitcnt lgkmcnt(3)
	s_waitcnt vmcnt(31)
	v_pk_fma_f32 v[4:5], v[164:165], v[36:37], v[4:5] op_sel_hi:[1,0,1]
	v_pk_fma_f32 v[6:7], v[166:167], v[36:37], v[6:7] op_sel_hi:[1,0,1]
	v_pk_fma_f32 v[12:13], v[164:165], v[40:41], v[12:13] op_sel_hi:[1,0,1]
	v_pk_fma_f32 v[14:15], v[166:167], v[40:41], v[14:15] op_sel_hi:[1,0,1]
	v_pk_fma_f32 v[8:9], v[164:165], v[0:1], v[8:9] op_sel_hi:[1,0,1]
	v_pk_fma_f32 v[10:11], v[166:167], v[0:1], v[10:11] op_sel_hi:[1,0,1]
	global_load_dwordx4 v[164:167], v[18:19], off
	v_lshl_add_u64 v[18:19], v[18:19], 0, s[40:41]
	s_waitcnt vmcnt(31)
	v_pk_fma_f32 v[4:5], v[202:203], v[36:37], v[4:5] op_sel:[0,1,0]
	v_pk_fma_f32 v[6:7], v[204:205], v[36:37], v[6:7] op_sel:[0,1,0]
	v_pk_fma_f32 v[12:13], v[202:203], v[40:41], v[12:13] op_sel:[0,1,0]
	v_pk_fma_f32 v[14:15], v[204:205], v[40:41], v[14:15] op_sel:[0,1,0]
	v_pk_fma_f32 v[8:9], v[202:203], v[0:1], v[8:9] op_sel:[0,1,0]
	v_pk_fma_f32 v[10:11], v[204:205], v[0:1], v[10:11] op_sel:[0,1,0]
	global_load_dwordx4 v[202:205], v[18:19], off
	v_lshl_add_u64 v[18:19], v[18:19], 0, s[40:41]
	s_waitcnt vmcnt(31)
	v_pk_fma_f32 v[4:5], v[206:207], v[38:39], v[4:5] op_sel_hi:[1,0,1]
	v_pk_fma_f32 v[6:7], v[208:209], v[38:39], v[6:7] op_sel_hi:[1,0,1]
	v_pk_fma_f32 v[12:13], v[206:207], v[42:43], v[12:13] op_sel_hi:[1,0,1]
	v_pk_fma_f32 v[14:15], v[208:209], v[42:43], v[14:15] op_sel_hi:[1,0,1]
	v_pk_fma_f32 v[8:9], v[206:207], v[2:3], v[8:9] op_sel_hi:[1,0,1]
	v_pk_fma_f32 v[10:11], v[208:209], v[2:3], v[10:11] op_sel_hi:[1,0,1]
	global_load_dwordx4 v[206:209], v[18:19], off
	v_lshl_add_u64 v[18:19], v[18:19], 0, s[40:41]
	s_waitcnt vmcnt(31)
	v_pk_fma_f32 v[4:5], v[210:211], v[38:39], v[4:5] op_sel:[0,1,0]
	v_pk_fma_f32 v[6:7], v[212:213], v[38:39], v[6:7] op_sel:[0,1,0]
	v_pk_fma_f32 v[12:13], v[210:211], v[42:43], v[12:13] op_sel:[0,1,0]
	v_pk_fma_f32 v[14:15], v[212:213], v[42:43], v[14:15] op_sel:[0,1,0]
	v_pk_fma_f32 v[8:9], v[210:211], v[2:3], v[8:9] op_sel:[0,1,0]
	v_pk_fma_f32 v[10:11], v[212:213], v[2:3], v[10:11] op_sel:[0,1,0]
	global_load_dwordx4 v[210:213], v[18:19], off
	v_lshl_add_u64 v[18:19], v[18:19], 0, s[40:41]
	ds_read_b128 v[36:39], v23 offset:144
	ds_read_b128 v[40:43], v23 offset:4240
	ds_read_b128 v[0:3], v23 offset:8336
	s_waitcnt lgkmcnt(3)
	s_waitcnt vmcnt(31)
	v_pk_fma_f32 v[4:5], v[44:45], v[24:25], v[4:5] op_sel_hi:[1,0,1]
	v_pk_fma_f32 v[6:7], v[46:47], v[24:25], v[6:7] op_sel_hi:[1,0,1]
	v_pk_fma_f32 v[12:13], v[44:45], v[28:29], v[12:13] op_sel_hi:[1,0,1]
	v_pk_fma_f32 v[14:15], v[46:47], v[28:29], v[14:15] op_sel_hi:[1,0,1]
	v_pk_fma_f32 v[8:9], v[44:45], v[32:33], v[8:9] op_sel_hi:[1,0,1]
	v_pk_fma_f32 v[10:11], v[46:47], v[32:33], v[10:11] op_sel_hi:[1,0,1]
	global_load_dwordx4 v[44:47], v[18:19], off
	v_lshl_add_u64 v[18:19], v[18:19], 0, s[40:41]
	s_waitcnt vmcnt(31)
	v_pk_fma_f32 v[4:5], v[48:49], v[24:25], v[4:5] op_sel:[0,1,0]
	v_pk_fma_f32 v[6:7], v[50:51], v[24:25], v[6:7] op_sel:[0,1,0]
	v_pk_fma_f32 v[12:13], v[48:49], v[28:29], v[12:13] op_sel:[0,1,0]
	v_pk_fma_f32 v[14:15], v[50:51], v[28:29], v[14:15] op_sel:[0,1,0]
	v_pk_fma_f32 v[8:9], v[48:49], v[32:33], v[8:9] op_sel:[0,1,0]
	v_pk_fma_f32 v[10:11], v[50:51], v[32:33], v[10:11] op_sel:[0,1,0]
	global_load_dwordx4 v[48:51], v[18:19], off
	v_lshl_add_u64 v[18:19], v[18:19], 0, s[40:41]
	s_waitcnt vmcnt(31)
	v_pk_fma_f32 v[4:5], v[52:53], v[26:27], v[4:5] op_sel_hi:[1,0,1]
	v_pk_fma_f32 v[6:7], v[54:55], v[26:27], v[6:7] op_sel_hi:[1,0,1]
	v_pk_fma_f32 v[12:13], v[52:53], v[30:31], v[12:13] op_sel_hi:[1,0,1]
	v_pk_fma_f32 v[14:15], v[54:55], v[30:31], v[14:15] op_sel_hi:[1,0,1]
	v_pk_fma_f32 v[8:9], v[52:53], v[34:35], v[8:9] op_sel_hi:[1,0,1]
	v_pk_fma_f32 v[10:11], v[54:55], v[34:35], v[10:11] op_sel_hi:[1,0,1]
	global_load_dwordx4 v[52:55], v[18:19], off
	v_lshl_add_u64 v[18:19], v[18:19], 0, s[40:41]
	s_waitcnt vmcnt(31)
	v_pk_fma_f32 v[4:5], v[56:57], v[26:27], v[4:5] op_sel:[0,1,0]
	v_pk_fma_f32 v[6:7], v[58:59], v[26:27], v[6:7] op_sel:[0,1,0]
	v_pk_fma_f32 v[12:13], v[56:57], v[30:31], v[12:13] op_sel:[0,1,0]
	v_pk_fma_f32 v[14:15], v[58:59], v[30:31], v[14:15] op_sel:[0,1,0]
	v_pk_fma_f32 v[8:9], v[56:57], v[34:35], v[8:9] op_sel:[0,1,0]
	v_pk_fma_f32 v[10:11], v[58:59], v[34:35], v[10:11] op_sel:[0,1,0]
	global_load_dwordx4 v[56:59], v[18:19], off
	v_lshl_add_u64 v[18:19], v[18:19], 0, s[40:41]
	ds_read_b128 v[24:27], v23 offset:160
	ds_read_b128 v[28:31], v23 offset:4256
	ds_read_b128 v[32:35], v23 offset:8352
	s_waitcnt lgkmcnt(3)
	s_waitcnt vmcnt(31)
	v_pk_fma_f32 v[4:5], v[60:61], v[36:37], v[4:5] op_sel_hi:[1,0,1]
	v_pk_fma_f32 v[6:7], v[62:63], v[36:37], v[6:7] op_sel_hi:[1,0,1]
	v_pk_fma_f32 v[12:13], v[60:61], v[40:41], v[12:13] op_sel_hi:[1,0,1]
	v_pk_fma_f32 v[14:15], v[62:63], v[40:41], v[14:15] op_sel_hi:[1,0,1]
	v_pk_fma_f32 v[8:9], v[60:61], v[0:1], v[8:9] op_sel_hi:[1,0,1]
	v_pk_fma_f32 v[10:11], v[62:63], v[0:1], v[10:11] op_sel_hi:[1,0,1]
	global_load_dwordx4 v[60:63], v[18:19], off
	v_lshl_add_u64 v[18:19], v[18:19], 0, s[40:41]
	s_waitcnt vmcnt(31)
	v_pk_fma_f32 v[4:5], v[64:65], v[36:37], v[4:5] op_sel:[0,1,0]
	v_pk_fma_f32 v[6:7], v[66:67], v[36:37], v[6:7] op_sel:[0,1,0]
	v_pk_fma_f32 v[12:13], v[64:65], v[40:41], v[12:13] op_sel:[0,1,0]
	v_pk_fma_f32 v[14:15], v[66:67], v[40:41], v[14:15] op_sel:[0,1,0]
	v_pk_fma_f32 v[8:9], v[64:65], v[0:1], v[8:9] op_sel:[0,1,0]
	v_pk_fma_f32 v[10:11], v[66:67], v[0:1], v[10:11] op_sel:[0,1,0]
	global_load_dwordx4 v[64:67], v[18:19], off
	v_lshl_add_u64 v[18:19], v[18:19], 0, s[40:41]
	s_waitcnt vmcnt(31)
	v_pk_fma_f32 v[4:5], v[68:69], v[38:39], v[4:5] op_sel_hi:[1,0,1]
	v_pk_fma_f32 v[6:7], v[70:71], v[38:39], v[6:7] op_sel_hi:[1,0,1]
	v_pk_fma_f32 v[12:13], v[68:69], v[42:43], v[12:13] op_sel_hi:[1,0,1]
	v_pk_fma_f32 v[14:15], v[70:71], v[42:43], v[14:15] op_sel_hi:[1,0,1]
	v_pk_fma_f32 v[8:9], v[68:69], v[2:3], v[8:9] op_sel_hi:[1,0,1]
	v_pk_fma_f32 v[10:11], v[70:71], v[2:3], v[10:11] op_sel_hi:[1,0,1]
	global_load_dwordx4 v[68:71], v[18:19], off
	v_lshl_add_u64 v[18:19], v[18:19], 0, s[40:41]
	s_waitcnt vmcnt(31)
	v_pk_fma_f32 v[4:5], v[72:73], v[38:39], v[4:5] op_sel:[0,1,0]
	v_pk_fma_f32 v[6:7], v[74:75], v[38:39], v[6:7] op_sel:[0,1,0]
	v_pk_fma_f32 v[12:13], v[72:73], v[42:43], v[12:13] op_sel:[0,1,0]
	v_pk_fma_f32 v[14:15], v[74:75], v[42:43], v[14:15] op_sel:[0,1,0]
	v_pk_fma_f32 v[8:9], v[72:73], v[2:3], v[8:9] op_sel:[0,1,0]
	v_pk_fma_f32 v[10:11], v[74:75], v[2:3], v[10:11] op_sel:[0,1,0]
	global_load_dwordx4 v[72:75], v[18:19], off
	v_lshl_add_u64 v[18:19], v[18:19], 0, s[40:41]
	ds_read_b128 v[36:39], v23 offset:176
	ds_read_b128 v[40:43], v23 offset:4272
	ds_read_b128 v[0:3], v23 offset:8368
	s_waitcnt lgkmcnt(3)
	s_waitcnt vmcnt(31)
	v_pk_fma_f32 v[4:5], v[76:77], v[24:25], v[4:5] op_sel_hi:[1,0,1]
	v_pk_fma_f32 v[6:7], v[78:79], v[24:25], v[6:7] op_sel_hi:[1,0,1]
	v_pk_fma_f32 v[12:13], v[76:77], v[28:29], v[12:13] op_sel_hi:[1,0,1]
	v_pk_fma_f32 v[14:15], v[78:79], v[28:29], v[14:15] op_sel_hi:[1,0,1]
	v_pk_fma_f32 v[8:9], v[76:77], v[32:33], v[8:9] op_sel_hi:[1,0,1]
	v_pk_fma_f32 v[10:11], v[78:79], v[32:33], v[10:11] op_sel_hi:[1,0,1]
	global_load_dwordx4 v[76:79], v[18:19], off
	v_lshl_add_u64 v[18:19], v[18:19], 0, s[40:41]
	s_waitcnt vmcnt(31)
	v_pk_fma_f32 v[4:5], v[80:81], v[24:25], v[4:5] op_sel:[0,1,0]
	v_pk_fma_f32 v[6:7], v[82:83], v[24:25], v[6:7] op_sel:[0,1,0]
	v_pk_fma_f32 v[12:13], v[80:81], v[28:29], v[12:13] op_sel:[0,1,0]
	v_pk_fma_f32 v[14:15], v[82:83], v[28:29], v[14:15] op_sel:[0,1,0]
	v_pk_fma_f32 v[8:9], v[80:81], v[32:33], v[8:9] op_sel:[0,1,0]
	v_pk_fma_f32 v[10:11], v[82:83], v[32:33], v[10:11] op_sel:[0,1,0]
	global_load_dwordx4 v[80:83], v[18:19], off
	v_lshl_add_u64 v[18:19], v[18:19], 0, s[40:41]
	s_waitcnt vmcnt(31)
	v_pk_fma_f32 v[4:5], v[84:85], v[26:27], v[4:5] op_sel_hi:[1,0,1]
	v_pk_fma_f32 v[6:7], v[86:87], v[26:27], v[6:7] op_sel_hi:[1,0,1]
	v_pk_fma_f32 v[12:13], v[84:85], v[30:31], v[12:13] op_sel_hi:[1,0,1]
	v_pk_fma_f32 v[14:15], v[86:87], v[30:31], v[14:15] op_sel_hi:[1,0,1]
	v_pk_fma_f32 v[8:9], v[84:85], v[34:35], v[8:9] op_sel_hi:[1,0,1]
	v_pk_fma_f32 v[10:11], v[86:87], v[34:35], v[10:11] op_sel_hi:[1,0,1]
	global_load_dwordx4 v[84:87], v[18:19], off
	v_lshl_add_u64 v[18:19], v[18:19], 0, s[40:41]
	s_waitcnt vmcnt(31)
	v_pk_fma_f32 v[4:5], v[88:89], v[26:27], v[4:5] op_sel:[0,1,0]
	v_pk_fma_f32 v[6:7], v[90:91], v[26:27], v[6:7] op_sel:[0,1,0]
	v_pk_fma_f32 v[12:13], v[88:89], v[30:31], v[12:13] op_sel:[0,1,0]
	v_pk_fma_f32 v[14:15], v[90:91], v[30:31], v[14:15] op_sel:[0,1,0]
	v_pk_fma_f32 v[8:9], v[88:89], v[34:35], v[8:9] op_sel:[0,1,0]
	v_pk_fma_f32 v[10:11], v[90:91], v[34:35], v[10:11] op_sel:[0,1,0]
	global_load_dwordx4 v[88:91], v[18:19], off
	v_lshl_add_u64 v[18:19], v[18:19], 0, s[40:41]
	ds_read_b128 v[24:27], v23 offset:192
	ds_read_b128 v[28:31], v23 offset:4288
	ds_read_b128 v[32:35], v23 offset:8384
	s_waitcnt lgkmcnt(3)
	s_waitcnt vmcnt(31)
	v_pk_fma_f32 v[4:5], v[92:93], v[36:37], v[4:5] op_sel_hi:[1,0,1]
	v_pk_fma_f32 v[6:7], v[94:95], v[36:37], v[6:7] op_sel_hi:[1,0,1]
	v_pk_fma_f32 v[12:13], v[92:93], v[40:41], v[12:13] op_sel_hi:[1,0,1]
	v_pk_fma_f32 v[14:15], v[94:95], v[40:41], v[14:15] op_sel_hi:[1,0,1]
	v_pk_fma_f32 v[8:9], v[92:93], v[0:1], v[8:9] op_sel_hi:[1,0,1]
	v_pk_fma_f32 v[10:11], v[94:95], v[0:1], v[10:11] op_sel_hi:[1,0,1]
	global_load_dwordx4 v[92:95], v[18:19], off
	v_lshl_add_u64 v[18:19], v[18:19], 0, s[40:41]
	s_waitcnt vmcnt(31)
	v_pk_fma_f32 v[4:5], v[96:97], v[36:37], v[4:5] op_sel:[0,1,0]
	v_pk_fma_f32 v[6:7], v[98:99], v[36:37], v[6:7] op_sel:[0,1,0]
	v_pk_fma_f32 v[12:13], v[96:97], v[40:41], v[12:13] op_sel:[0,1,0]
	v_pk_fma_f32 v[14:15], v[98:99], v[40:41], v[14:15] op_sel:[0,1,0]
	v_pk_fma_f32 v[8:9], v[96:97], v[0:1], v[8:9] op_sel:[0,1,0]
	v_pk_fma_f32 v[10:11], v[98:99], v[0:1], v[10:11] op_sel:[0,1,0]
	global_load_dwordx4 v[96:99], v[18:19], off
	v_lshl_add_u64 v[18:19], v[18:19], 0, s[40:41]
	s_waitcnt vmcnt(31)
	v_pk_fma_f32 v[4:5], v[100:101], v[38:39], v[4:5] op_sel_hi:[1,0,1]
	v_pk_fma_f32 v[6:7], v[102:103], v[38:39], v[6:7] op_sel_hi:[1,0,1]
	v_pk_fma_f32 v[12:13], v[100:101], v[42:43], v[12:13] op_sel_hi:[1,0,1]
	v_pk_fma_f32 v[14:15], v[102:103], v[42:43], v[14:15] op_sel_hi:[1,0,1]
	v_pk_fma_f32 v[8:9], v[100:101], v[2:3], v[8:9] op_sel_hi:[1,0,1]
	v_pk_fma_f32 v[10:11], v[102:103], v[2:3], v[10:11] op_sel_hi:[1,0,1]
	global_load_dwordx4 v[100:103], v[18:19], off
	v_lshl_add_u64 v[18:19], v[18:19], 0, s[40:41]
	s_waitcnt vmcnt(31)
	v_pk_fma_f32 v[4:5], v[104:105], v[38:39], v[4:5] op_sel:[0,1,0]
	v_pk_fma_f32 v[6:7], v[106:107], v[38:39], v[6:7] op_sel:[0,1,0]
	v_pk_fma_f32 v[12:13], v[104:105], v[42:43], v[12:13] op_sel:[0,1,0]
	v_pk_fma_f32 v[14:15], v[106:107], v[42:43], v[14:15] op_sel:[0,1,0]
	v_pk_fma_f32 v[8:9], v[104:105], v[2:3], v[8:9] op_sel:[0,1,0]
	v_pk_fma_f32 v[10:11], v[106:107], v[2:3], v[10:11] op_sel:[0,1,0]
	global_load_dwordx4 v[104:107], v[18:19], off
	v_lshl_add_u64 v[18:19], v[18:19], 0, s[40:41]
	ds_read_b128 v[36:39], v23 offset:208
	ds_read_b128 v[40:43], v23 offset:4304
	ds_read_b128 v[0:3], v23 offset:8400
	s_waitcnt lgkmcnt(3)
	s_waitcnt vmcnt(31)
	v_pk_fma_f32 v[4:5], v[108:109], v[24:25], v[4:5] op_sel_hi:[1,0,1]
	v_pk_fma_f32 v[6:7], v[110:111], v[24:25], v[6:7] op_sel_hi:[1,0,1]
	v_pk_fma_f32 v[12:13], v[108:109], v[28:29], v[12:13] op_sel_hi:[1,0,1]
	v_pk_fma_f32 v[14:15], v[110:111], v[28:29], v[14:15] op_sel_hi:[1,0,1]
	v_pk_fma_f32 v[8:9], v[108:109], v[32:33], v[8:9] op_sel_hi:[1,0,1]
	v_pk_fma_f32 v[10:11], v[110:111], v[32:33], v[10:11] op_sel_hi:[1,0,1]
	global_load_dwordx4 v[108:111], v[18:19], off
	v_lshl_add_u64 v[18:19], v[18:19], 0, s[40:41]
	s_waitcnt vmcnt(31)
	v_pk_fma_f32 v[4:5], v[112:113], v[24:25], v[4:5] op_sel:[0,1,0]
	v_pk_fma_f32 v[6:7], v[114:115], v[24:25], v[6:7] op_sel:[0,1,0]
	v_pk_fma_f32 v[12:13], v[112:113], v[28:29], v[12:13] op_sel:[0,1,0]
	v_pk_fma_f32 v[14:15], v[114:115], v[28:29], v[14:15] op_sel:[0,1,0]
	v_pk_fma_f32 v[8:9], v[112:113], v[32:33], v[8:9] op_sel:[0,1,0]
	v_pk_fma_f32 v[10:11], v[114:115], v[32:33], v[10:11] op_sel:[0,1,0]
	global_load_dwordx4 v[112:115], v[18:19], off
	v_lshl_add_u64 v[18:19], v[18:19], 0, s[40:41]
	s_waitcnt vmcnt(31)
	v_pk_fma_f32 v[4:5], v[116:117], v[26:27], v[4:5] op_sel_hi:[1,0,1]
	v_pk_fma_f32 v[6:7], v[118:119], v[26:27], v[6:7] op_sel_hi:[1,0,1]
	v_pk_fma_f32 v[12:13], v[116:117], v[30:31], v[12:13] op_sel_hi:[1,0,1]
	v_pk_fma_f32 v[14:15], v[118:119], v[30:31], v[14:15] op_sel_hi:[1,0,1]
	v_pk_fma_f32 v[8:9], v[116:117], v[34:35], v[8:9] op_sel_hi:[1,0,1]
	v_pk_fma_f32 v[10:11], v[118:119], v[34:35], v[10:11] op_sel_hi:[1,0,1]
	global_load_dwordx4 v[116:119], v[18:19], off
	v_lshl_add_u64 v[18:19], v[18:19], 0, s[40:41]
	s_waitcnt vmcnt(31)
	v_pk_fma_f32 v[4:5], v[120:121], v[26:27], v[4:5] op_sel:[0,1,0]
	v_pk_fma_f32 v[6:7], v[122:123], v[26:27], v[6:7] op_sel:[0,1,0]
	v_pk_fma_f32 v[12:13], v[120:121], v[30:31], v[12:13] op_sel:[0,1,0]
	v_pk_fma_f32 v[14:15], v[122:123], v[30:31], v[14:15] op_sel:[0,1,0]
	v_pk_fma_f32 v[8:9], v[120:121], v[34:35], v[8:9] op_sel:[0,1,0]
	v_pk_fma_f32 v[10:11], v[122:123], v[34:35], v[10:11] op_sel:[0,1,0]
	global_load_dwordx4 v[120:123], v[18:19], off
	v_lshl_add_u64 v[18:19], v[18:19], 0, s[40:41]
	ds_read_b128 v[24:27], v23 offset:224
	ds_read_b128 v[28:31], v23 offset:4320
	ds_read_b128 v[32:35], v23 offset:8416
	s_waitcnt lgkmcnt(3)
	s_waitcnt vmcnt(31)
	v_pk_fma_f32 v[4:5], v[124:125], v[36:37], v[4:5] op_sel_hi:[1,0,1]
	v_pk_fma_f32 v[6:7], v[126:127], v[36:37], v[6:7] op_sel_hi:[1,0,1]
	v_pk_fma_f32 v[12:13], v[124:125], v[40:41], v[12:13] op_sel_hi:[1,0,1]
	v_pk_fma_f32 v[14:15], v[126:127], v[40:41], v[14:15] op_sel_hi:[1,0,1]
	v_pk_fma_f32 v[8:9], v[124:125], v[0:1], v[8:9] op_sel_hi:[1,0,1]
	v_pk_fma_f32 v[10:11], v[126:127], v[0:1], v[10:11] op_sel_hi:[1,0,1]
	global_load_dwordx4 v[124:127], v[18:19], off
	v_lshl_add_u64 v[18:19], v[18:19], 0, s[40:41]
	s_waitcnt vmcnt(31)
	v_pk_fma_f32 v[4:5], v[136:137], v[36:37], v[4:5] op_sel:[0,1,0]
	v_pk_fma_f32 v[6:7], v[138:139], v[36:37], v[6:7] op_sel:[0,1,0]
	v_pk_fma_f32 v[12:13], v[136:137], v[40:41], v[12:13] op_sel:[0,1,0]
	v_pk_fma_f32 v[14:15], v[138:139], v[40:41], v[14:15] op_sel:[0,1,0]
	v_pk_fma_f32 v[8:9], v[136:137], v[0:1], v[8:9] op_sel:[0,1,0]
	v_pk_fma_f32 v[10:11], v[138:139], v[0:1], v[10:11] op_sel:[0,1,0]
	global_load_dwordx4 v[136:139], v[18:19], off
	v_lshl_add_u64 v[18:19], v[18:19], 0, s[40:41]
	s_waitcnt vmcnt(31)
	v_pk_fma_f32 v[4:5], v[140:141], v[38:39], v[4:5] op_sel_hi:[1,0,1]
	v_pk_fma_f32 v[6:7], v[142:143], v[38:39], v[6:7] op_sel_hi:[1,0,1]
	v_pk_fma_f32 v[12:13], v[140:141], v[42:43], v[12:13] op_sel_hi:[1,0,1]
	v_pk_fma_f32 v[14:15], v[142:143], v[42:43], v[14:15] op_sel_hi:[1,0,1]
	v_pk_fma_f32 v[8:9], v[140:141], v[2:3], v[8:9] op_sel_hi:[1,0,1]
	v_pk_fma_f32 v[10:11], v[142:143], v[2:3], v[10:11] op_sel_hi:[1,0,1]
	global_load_dwordx4 v[140:143], v[18:19], off
	v_lshl_add_u64 v[18:19], v[18:19], 0, s[40:41]
	s_waitcnt vmcnt(31)
	v_pk_fma_f32 v[4:5], v[144:145], v[38:39], v[4:5] op_sel:[0,1,0]
	v_pk_fma_f32 v[6:7], v[146:147], v[38:39], v[6:7] op_sel:[0,1,0]
	v_pk_fma_f32 v[12:13], v[144:145], v[42:43], v[12:13] op_sel:[0,1,0]
	v_pk_fma_f32 v[14:15], v[146:147], v[42:43], v[14:15] op_sel:[0,1,0]
	v_pk_fma_f32 v[8:9], v[144:145], v[2:3], v[8:9] op_sel:[0,1,0]
	v_pk_fma_f32 v[10:11], v[146:147], v[2:3], v[10:11] op_sel:[0,1,0]
	global_load_dwordx4 v[144:147], v[18:19], off
	v_lshl_add_u64 v[18:19], v[18:19], 0, s[40:41]
	ds_read_b128 v[36:39], v23 offset:240
	ds_read_b128 v[40:43], v23 offset:4336
	ds_read_b128 v[0:3], v23 offset:8432
	s_waitcnt lgkmcnt(3)
	s_waitcnt vmcnt(31)
	v_pk_fma_f32 v[4:5], v[148:149], v[24:25], v[4:5] op_sel_hi:[1,0,1]
	v_pk_fma_f32 v[6:7], v[150:151], v[24:25], v[6:7] op_sel_hi:[1,0,1]
	v_pk_fma_f32 v[12:13], v[148:149], v[28:29], v[12:13] op_sel_hi:[1,0,1]
	v_pk_fma_f32 v[14:15], v[150:151], v[28:29], v[14:15] op_sel_hi:[1,0,1]
	v_pk_fma_f32 v[8:9], v[148:149], v[32:33], v[8:9] op_sel_hi:[1,0,1]
	v_pk_fma_f32 v[10:11], v[150:151], v[32:33], v[10:11] op_sel_hi:[1,0,1]
	global_load_dwordx4 v[148:151], v[18:19], off
	v_lshl_add_u64 v[18:19], v[18:19], 0, s[40:41]
	s_waitcnt vmcnt(31)
	v_pk_fma_f32 v[4:5], v[152:153], v[24:25], v[4:5] op_sel:[0,1,0]
	v_pk_fma_f32 v[6:7], v[154:155], v[24:25], v[6:7] op_sel:[0,1,0]
	v_pk_fma_f32 v[12:13], v[152:153], v[28:29], v[12:13] op_sel:[0,1,0]
	v_pk_fma_f32 v[14:15], v[154:155], v[28:29], v[14:15] op_sel:[0,1,0]
	v_pk_fma_f32 v[8:9], v[152:153], v[32:33], v[8:9] op_sel:[0,1,0]
	v_pk_fma_f32 v[10:11], v[154:155], v[32:33], v[10:11] op_sel:[0,1,0]
	global_load_dwordx4 v[152:155], v[18:19], off
	v_lshl_add_u64 v[18:19], v[18:19], 0, s[40:41]
	s_waitcnt vmcnt(31)
	v_pk_fma_f32 v[4:5], v[156:157], v[26:27], v[4:5] op_sel_hi:[1,0,1]
	v_pk_fma_f32 v[6:7], v[158:159], v[26:27], v[6:7] op_sel_hi:[1,0,1]
	v_pk_fma_f32 v[12:13], v[156:157], v[30:31], v[12:13] op_sel_hi:[1,0,1]
	v_pk_fma_f32 v[14:15], v[158:159], v[30:31], v[14:15] op_sel_hi:[1,0,1]
	v_pk_fma_f32 v[8:9], v[156:157], v[34:35], v[8:9] op_sel_hi:[1,0,1]
	v_pk_fma_f32 v[10:11], v[158:159], v[34:35], v[10:11] op_sel_hi:[1,0,1]
	global_load_dwordx4 v[156:159], v[18:19], off
	v_lshl_add_u64 v[18:19], v[18:19], 0, s[40:41]
	s_waitcnt vmcnt(31)
	v_pk_fma_f32 v[4:5], v[160:161], v[26:27], v[4:5] op_sel:[0,1,0]
	v_pk_fma_f32 v[6:7], v[162:163], v[26:27], v[6:7] op_sel:[0,1,0]
	v_pk_fma_f32 v[12:13], v[160:161], v[30:31], v[12:13] op_sel:[0,1,0]
	v_pk_fma_f32 v[14:15], v[162:163], v[30:31], v[14:15] op_sel:[0,1,0]
	v_pk_fma_f32 v[8:9], v[160:161], v[34:35], v[8:9] op_sel:[0,1,0]
	v_pk_fma_f32 v[10:11], v[162:163], v[34:35], v[10:11] op_sel:[0,1,0]
	global_load_dwordx4 v[160:163], v[18:19], off
	v_lshl_add_u64 v[18:19], v[18:19], 0, s[40:41]
	ds_read_b128 v[24:27], v23 offset:256
	ds_read_b128 v[28:31], v23 offset:4352
	ds_read_b128 v[32:35], v23 offset:8448
	s_waitcnt lgkmcnt(3)
	s_waitcnt vmcnt(31)
	v_pk_fma_f32 v[4:5], v[164:165], v[36:37], v[4:5] op_sel_hi:[1,0,1]
	v_pk_fma_f32 v[6:7], v[166:167], v[36:37], v[6:7] op_sel_hi:[1,0,1]
	v_pk_fma_f32 v[12:13], v[164:165], v[40:41], v[12:13] op_sel_hi:[1,0,1]
	v_pk_fma_f32 v[14:15], v[166:167], v[40:41], v[14:15] op_sel_hi:[1,0,1]
	v_pk_fma_f32 v[8:9], v[164:165], v[0:1], v[8:9] op_sel_hi:[1,0,1]
	v_pk_fma_f32 v[10:11], v[166:167], v[0:1], v[10:11] op_sel_hi:[1,0,1]
	global_load_dwordx4 v[164:167], v[18:19], off
	v_lshl_add_u64 v[18:19], v[18:19], 0, s[40:41]
	s_waitcnt vmcnt(31)
	v_pk_fma_f32 v[4:5], v[202:203], v[36:37], v[4:5] op_sel:[0,1,0]
	v_pk_fma_f32 v[6:7], v[204:205], v[36:37], v[6:7] op_sel:[0,1,0]
	v_pk_fma_f32 v[12:13], v[202:203], v[40:41], v[12:13] op_sel:[0,1,0]
	v_pk_fma_f32 v[14:15], v[204:205], v[40:41], v[14:15] op_sel:[0,1,0]
	v_pk_fma_f32 v[8:9], v[202:203], v[0:1], v[8:9] op_sel:[0,1,0]
	v_pk_fma_f32 v[10:11], v[204:205], v[0:1], v[10:11] op_sel:[0,1,0]
	global_load_dwordx4 v[202:205], v[18:19], off
	v_lshl_add_u64 v[18:19], v[18:19], 0, s[40:41]
	s_waitcnt vmcnt(31)
	v_pk_fma_f32 v[4:5], v[206:207], v[38:39], v[4:5] op_sel_hi:[1,0,1]
	v_pk_fma_f32 v[6:7], v[208:209], v[38:39], v[6:7] op_sel_hi:[1,0,1]
	v_pk_fma_f32 v[12:13], v[206:207], v[42:43], v[12:13] op_sel_hi:[1,0,1]
	v_pk_fma_f32 v[14:15], v[208:209], v[42:43], v[14:15] op_sel_hi:[1,0,1]
	v_pk_fma_f32 v[8:9], v[206:207], v[2:3], v[8:9] op_sel_hi:[1,0,1]
	v_pk_fma_f32 v[10:11], v[208:209], v[2:3], v[10:11] op_sel_hi:[1,0,1]
	global_load_dwordx4 v[206:209], v[18:19], off
	v_lshl_add_u64 v[18:19], v[18:19], 0, s[40:41]
	s_waitcnt vmcnt(31)
	v_pk_fma_f32 v[4:5], v[210:211], v[38:39], v[4:5] op_sel:[0,1,0]
	v_pk_fma_f32 v[6:7], v[212:213], v[38:39], v[6:7] op_sel:[0,1,0]
	v_pk_fma_f32 v[12:13], v[210:211], v[42:43], v[12:13] op_sel:[0,1,0]
	v_pk_fma_f32 v[14:15], v[212:213], v[42:43], v[14:15] op_sel:[0,1,0]
	v_pk_fma_f32 v[8:9], v[210:211], v[2:3], v[8:9] op_sel:[0,1,0]
	v_pk_fma_f32 v[10:11], v[212:213], v[2:3], v[10:11] op_sel:[0,1,0]
	global_load_dwordx4 v[210:213], v[18:19], off
	v_lshl_add_u64 v[18:19], v[18:19], 0, s[40:41]
	ds_read_b128 v[36:39], v23 offset:272
	ds_read_b128 v[40:43], v23 offset:4368
	ds_read_b128 v[0:3], v23 offset:8464
	s_waitcnt lgkmcnt(3)
	s_waitcnt vmcnt(31)
	v_pk_fma_f32 v[4:5], v[44:45], v[24:25], v[4:5] op_sel_hi:[1,0,1]
	v_pk_fma_f32 v[6:7], v[46:47], v[24:25], v[6:7] op_sel_hi:[1,0,1]
	v_pk_fma_f32 v[12:13], v[44:45], v[28:29], v[12:13] op_sel_hi:[1,0,1]
	v_pk_fma_f32 v[14:15], v[46:47], v[28:29], v[14:15] op_sel_hi:[1,0,1]
	v_pk_fma_f32 v[8:9], v[44:45], v[32:33], v[8:9] op_sel_hi:[1,0,1]
	v_pk_fma_f32 v[10:11], v[46:47], v[32:33], v[10:11] op_sel_hi:[1,0,1]
	global_load_dwordx4 v[44:47], v[18:19], off
	v_lshl_add_u64 v[18:19], v[18:19], 0, s[40:41]
	s_waitcnt vmcnt(31)
	v_pk_fma_f32 v[4:5], v[48:49], v[24:25], v[4:5] op_sel:[0,1,0]
	v_pk_fma_f32 v[6:7], v[50:51], v[24:25], v[6:7] op_sel:[0,1,0]
	v_pk_fma_f32 v[12:13], v[48:49], v[28:29], v[12:13] op_sel:[0,1,0]
	v_pk_fma_f32 v[14:15], v[50:51], v[28:29], v[14:15] op_sel:[0,1,0]
	v_pk_fma_f32 v[8:9], v[48:49], v[32:33], v[8:9] op_sel:[0,1,0]
	v_pk_fma_f32 v[10:11], v[50:51], v[32:33], v[10:11] op_sel:[0,1,0]
	global_load_dwordx4 v[48:51], v[18:19], off
	v_lshl_add_u64 v[18:19], v[18:19], 0, s[40:41]
	s_waitcnt vmcnt(31)
	v_pk_fma_f32 v[4:5], v[52:53], v[26:27], v[4:5] op_sel_hi:[1,0,1]
	v_pk_fma_f32 v[6:7], v[54:55], v[26:27], v[6:7] op_sel_hi:[1,0,1]
	v_pk_fma_f32 v[12:13], v[52:53], v[30:31], v[12:13] op_sel_hi:[1,0,1]
	v_pk_fma_f32 v[14:15], v[54:55], v[30:31], v[14:15] op_sel_hi:[1,0,1]
	v_pk_fma_f32 v[8:9], v[52:53], v[34:35], v[8:9] op_sel_hi:[1,0,1]
	v_pk_fma_f32 v[10:11], v[54:55], v[34:35], v[10:11] op_sel_hi:[1,0,1]
	global_load_dwordx4 v[52:55], v[18:19], off
	v_lshl_add_u64 v[18:19], v[18:19], 0, s[40:41]
	s_waitcnt vmcnt(31)
	v_pk_fma_f32 v[4:5], v[56:57], v[26:27], v[4:5] op_sel:[0,1,0]
	v_pk_fma_f32 v[6:7], v[58:59], v[26:27], v[6:7] op_sel:[0,1,0]
	v_pk_fma_f32 v[12:13], v[56:57], v[30:31], v[12:13] op_sel:[0,1,0]
	v_pk_fma_f32 v[14:15], v[58:59], v[30:31], v[14:15] op_sel:[0,1,0]
	v_pk_fma_f32 v[8:9], v[56:57], v[34:35], v[8:9] op_sel:[0,1,0]
	v_pk_fma_f32 v[10:11], v[58:59], v[34:35], v[10:11] op_sel:[0,1,0]
	global_load_dwordx4 v[56:59], v[18:19], off
	v_lshl_add_u64 v[18:19], v[18:19], 0, s[40:41]
	ds_read_b128 v[24:27], v23 offset:288
	ds_read_b128 v[28:31], v23 offset:4384
	ds_read_b128 v[32:35], v23 offset:8480
	s_waitcnt lgkmcnt(3)
	s_waitcnt vmcnt(31)
	v_pk_fma_f32 v[4:5], v[60:61], v[36:37], v[4:5] op_sel_hi:[1,0,1]
	v_pk_fma_f32 v[6:7], v[62:63], v[36:37], v[6:7] op_sel_hi:[1,0,1]
	v_pk_fma_f32 v[12:13], v[60:61], v[40:41], v[12:13] op_sel_hi:[1,0,1]
	v_pk_fma_f32 v[14:15], v[62:63], v[40:41], v[14:15] op_sel_hi:[1,0,1]
	v_pk_fma_f32 v[8:9], v[60:61], v[0:1], v[8:9] op_sel_hi:[1,0,1]
	v_pk_fma_f32 v[10:11], v[62:63], v[0:1], v[10:11] op_sel_hi:[1,0,1]
	global_load_dwordx4 v[60:63], v[18:19], off
	v_lshl_add_u64 v[18:19], v[18:19], 0, s[40:41]
	s_waitcnt vmcnt(31)
	v_pk_fma_f32 v[4:5], v[64:65], v[36:37], v[4:5] op_sel:[0,1,0]
	v_pk_fma_f32 v[6:7], v[66:67], v[36:37], v[6:7] op_sel:[0,1,0]
	v_pk_fma_f32 v[12:13], v[64:65], v[40:41], v[12:13] op_sel:[0,1,0]
	v_pk_fma_f32 v[14:15], v[66:67], v[40:41], v[14:15] op_sel:[0,1,0]
	v_pk_fma_f32 v[8:9], v[64:65], v[0:1], v[8:9] op_sel:[0,1,0]
	v_pk_fma_f32 v[10:11], v[66:67], v[0:1], v[10:11] op_sel:[0,1,0]
	global_load_dwordx4 v[64:67], v[18:19], off
	v_lshl_add_u64 v[18:19], v[18:19], 0, s[40:41]
	s_waitcnt vmcnt(31)
	v_pk_fma_f32 v[4:5], v[68:69], v[38:39], v[4:5] op_sel_hi:[1,0,1]
	v_pk_fma_f32 v[6:7], v[70:71], v[38:39], v[6:7] op_sel_hi:[1,0,1]
	v_pk_fma_f32 v[12:13], v[68:69], v[42:43], v[12:13] op_sel_hi:[1,0,1]
	v_pk_fma_f32 v[14:15], v[70:71], v[42:43], v[14:15] op_sel_hi:[1,0,1]
	v_pk_fma_f32 v[8:9], v[68:69], v[2:3], v[8:9] op_sel_hi:[1,0,1]
	v_pk_fma_f32 v[10:11], v[70:71], v[2:3], v[10:11] op_sel_hi:[1,0,1]
	global_load_dwordx4 v[68:71], v[18:19], off
	v_lshl_add_u64 v[18:19], v[18:19], 0, s[40:41]
	s_waitcnt vmcnt(31)
	v_pk_fma_f32 v[4:5], v[72:73], v[38:39], v[4:5] op_sel:[0,1,0]
	v_pk_fma_f32 v[6:7], v[74:75], v[38:39], v[6:7] op_sel:[0,1,0]
	v_pk_fma_f32 v[12:13], v[72:73], v[42:43], v[12:13] op_sel:[0,1,0]
	v_pk_fma_f32 v[14:15], v[74:75], v[42:43], v[14:15] op_sel:[0,1,0]
	v_pk_fma_f32 v[8:9], v[72:73], v[2:3], v[8:9] op_sel:[0,1,0]
	v_pk_fma_f32 v[10:11], v[74:75], v[2:3], v[10:11] op_sel:[0,1,0]
	global_load_dwordx4 v[72:75], v[18:19], off
	v_lshl_add_u64 v[18:19], v[18:19], 0, s[40:41]
	ds_read_b128 v[36:39], v23 offset:304
	ds_read_b128 v[40:43], v23 offset:4400
	ds_read_b128 v[0:3], v23 offset:8496
	s_waitcnt lgkmcnt(3)
	s_waitcnt vmcnt(31)
	v_pk_fma_f32 v[4:5], v[76:77], v[24:25], v[4:5] op_sel_hi:[1,0,1]
	v_pk_fma_f32 v[6:7], v[78:79], v[24:25], v[6:7] op_sel_hi:[1,0,1]
	v_pk_fma_f32 v[12:13], v[76:77], v[28:29], v[12:13] op_sel_hi:[1,0,1]
	v_pk_fma_f32 v[14:15], v[78:79], v[28:29], v[14:15] op_sel_hi:[1,0,1]
	v_pk_fma_f32 v[8:9], v[76:77], v[32:33], v[8:9] op_sel_hi:[1,0,1]
	v_pk_fma_f32 v[10:11], v[78:79], v[32:33], v[10:11] op_sel_hi:[1,0,1]
	global_load_dwordx4 v[76:79], v[18:19], off
	v_lshl_add_u64 v[18:19], v[18:19], 0, s[40:41]
	s_waitcnt vmcnt(31)
	v_pk_fma_f32 v[4:5], v[80:81], v[24:25], v[4:5] op_sel:[0,1,0]
	v_pk_fma_f32 v[6:7], v[82:83], v[24:25], v[6:7] op_sel:[0,1,0]
	v_pk_fma_f32 v[12:13], v[80:81], v[28:29], v[12:13] op_sel:[0,1,0]
	v_pk_fma_f32 v[14:15], v[82:83], v[28:29], v[14:15] op_sel:[0,1,0]
	v_pk_fma_f32 v[8:9], v[80:81], v[32:33], v[8:9] op_sel:[0,1,0]
	v_pk_fma_f32 v[10:11], v[82:83], v[32:33], v[10:11] op_sel:[0,1,0]
	global_load_dwordx4 v[80:83], v[18:19], off
	v_lshl_add_u64 v[18:19], v[18:19], 0, s[40:41]
	s_waitcnt vmcnt(31)
	v_pk_fma_f32 v[4:5], v[84:85], v[26:27], v[4:5] op_sel_hi:[1,0,1]
	v_pk_fma_f32 v[6:7], v[86:87], v[26:27], v[6:7] op_sel_hi:[1,0,1]
	v_pk_fma_f32 v[12:13], v[84:85], v[30:31], v[12:13] op_sel_hi:[1,0,1]
	v_pk_fma_f32 v[14:15], v[86:87], v[30:31], v[14:15] op_sel_hi:[1,0,1]
	v_pk_fma_f32 v[8:9], v[84:85], v[34:35], v[8:9] op_sel_hi:[1,0,1]
	v_pk_fma_f32 v[10:11], v[86:87], v[34:35], v[10:11] op_sel_hi:[1,0,1]
	global_load_dwordx4 v[84:87], v[18:19], off
	v_lshl_add_u64 v[18:19], v[18:19], 0, s[40:41]
	s_waitcnt vmcnt(31)
	v_pk_fma_f32 v[4:5], v[88:89], v[26:27], v[4:5] op_sel:[0,1,0]
	v_pk_fma_f32 v[6:7], v[90:91], v[26:27], v[6:7] op_sel:[0,1,0]
	v_pk_fma_f32 v[12:13], v[88:89], v[30:31], v[12:13] op_sel:[0,1,0]
	v_pk_fma_f32 v[14:15], v[90:91], v[30:31], v[14:15] op_sel:[0,1,0]
	v_pk_fma_f32 v[8:9], v[88:89], v[34:35], v[8:9] op_sel:[0,1,0]
	v_pk_fma_f32 v[10:11], v[90:91], v[34:35], v[10:11] op_sel:[0,1,0]
	global_load_dwordx4 v[88:91], v[18:19], off
	v_lshl_add_u64 v[18:19], v[18:19], 0, s[40:41]
	ds_read_b128 v[24:27], v23 offset:320
	ds_read_b128 v[28:31], v23 offset:4416
	ds_read_b128 v[32:35], v23 offset:8512
	s_waitcnt lgkmcnt(3)
	s_waitcnt vmcnt(31)
	v_pk_fma_f32 v[4:5], v[92:93], v[36:37], v[4:5] op_sel_hi:[1,0,1]
	v_pk_fma_f32 v[6:7], v[94:95], v[36:37], v[6:7] op_sel_hi:[1,0,1]
	v_pk_fma_f32 v[12:13], v[92:93], v[40:41], v[12:13] op_sel_hi:[1,0,1]
	v_pk_fma_f32 v[14:15], v[94:95], v[40:41], v[14:15] op_sel_hi:[1,0,1]
	v_pk_fma_f32 v[8:9], v[92:93], v[0:1], v[8:9] op_sel_hi:[1,0,1]
	v_pk_fma_f32 v[10:11], v[94:95], v[0:1], v[10:11] op_sel_hi:[1,0,1]
	global_load_dwordx4 v[92:95], v[18:19], off
	v_lshl_add_u64 v[18:19], v[18:19], 0, s[40:41]
	s_waitcnt vmcnt(31)
	v_pk_fma_f32 v[4:5], v[96:97], v[36:37], v[4:5] op_sel:[0,1,0]
	v_pk_fma_f32 v[6:7], v[98:99], v[36:37], v[6:7] op_sel:[0,1,0]
	v_pk_fma_f32 v[12:13], v[96:97], v[40:41], v[12:13] op_sel:[0,1,0]
	v_pk_fma_f32 v[14:15], v[98:99], v[40:41], v[14:15] op_sel:[0,1,0]
	v_pk_fma_f32 v[8:9], v[96:97], v[0:1], v[8:9] op_sel:[0,1,0]
	v_pk_fma_f32 v[10:11], v[98:99], v[0:1], v[10:11] op_sel:[0,1,0]
	global_load_dwordx4 v[96:99], v[18:19], off
	v_lshl_add_u64 v[18:19], v[18:19], 0, s[40:41]
	s_waitcnt vmcnt(31)
	v_pk_fma_f32 v[4:5], v[100:101], v[38:39], v[4:5] op_sel_hi:[1,0,1]
	v_pk_fma_f32 v[6:7], v[102:103], v[38:39], v[6:7] op_sel_hi:[1,0,1]
	v_pk_fma_f32 v[12:13], v[100:101], v[42:43], v[12:13] op_sel_hi:[1,0,1]
	v_pk_fma_f32 v[14:15], v[102:103], v[42:43], v[14:15] op_sel_hi:[1,0,1]
	v_pk_fma_f32 v[8:9], v[100:101], v[2:3], v[8:9] op_sel_hi:[1,0,1]
	v_pk_fma_f32 v[10:11], v[102:103], v[2:3], v[10:11] op_sel_hi:[1,0,1]
	global_load_dwordx4 v[100:103], v[18:19], off
	v_lshl_add_u64 v[18:19], v[18:19], 0, s[40:41]
	s_waitcnt vmcnt(31)
	v_pk_fma_f32 v[4:5], v[104:105], v[38:39], v[4:5] op_sel:[0,1,0]
	v_pk_fma_f32 v[6:7], v[106:107], v[38:39], v[6:7] op_sel:[0,1,0]
	v_pk_fma_f32 v[12:13], v[104:105], v[42:43], v[12:13] op_sel:[0,1,0]
	v_pk_fma_f32 v[14:15], v[106:107], v[42:43], v[14:15] op_sel:[0,1,0]
	v_pk_fma_f32 v[8:9], v[104:105], v[2:3], v[8:9] op_sel:[0,1,0]
	v_pk_fma_f32 v[10:11], v[106:107], v[2:3], v[10:11] op_sel:[0,1,0]
	global_load_dwordx4 v[104:107], v[18:19], off
	v_lshl_add_u64 v[18:19], v[18:19], 0, s[40:41]
	ds_read_b128 v[36:39], v23 offset:336
	ds_read_b128 v[40:43], v23 offset:4432
	ds_read_b128 v[0:3], v23 offset:8528
	s_waitcnt lgkmcnt(3)
	s_waitcnt vmcnt(31)
	v_pk_fma_f32 v[4:5], v[108:109], v[24:25], v[4:5] op_sel_hi:[1,0,1]
	v_pk_fma_f32 v[6:7], v[110:111], v[24:25], v[6:7] op_sel_hi:[1,0,1]
	v_pk_fma_f32 v[12:13], v[108:109], v[28:29], v[12:13] op_sel_hi:[1,0,1]
	v_pk_fma_f32 v[14:15], v[110:111], v[28:29], v[14:15] op_sel_hi:[1,0,1]
	v_pk_fma_f32 v[8:9], v[108:109], v[32:33], v[8:9] op_sel_hi:[1,0,1]
	v_pk_fma_f32 v[10:11], v[110:111], v[32:33], v[10:11] op_sel_hi:[1,0,1]
	global_load_dwordx4 v[108:111], v[18:19], off
	v_lshl_add_u64 v[18:19], v[18:19], 0, s[40:41]
	s_waitcnt vmcnt(31)
	v_pk_fma_f32 v[4:5], v[112:113], v[24:25], v[4:5] op_sel:[0,1,0]
	v_pk_fma_f32 v[6:7], v[114:115], v[24:25], v[6:7] op_sel:[0,1,0]
	v_pk_fma_f32 v[12:13], v[112:113], v[28:29], v[12:13] op_sel:[0,1,0]
	v_pk_fma_f32 v[14:15], v[114:115], v[28:29], v[14:15] op_sel:[0,1,0]
	v_pk_fma_f32 v[8:9], v[112:113], v[32:33], v[8:9] op_sel:[0,1,0]
	v_pk_fma_f32 v[10:11], v[114:115], v[32:33], v[10:11] op_sel:[0,1,0]
	global_load_dwordx4 v[112:115], v[18:19], off
	v_lshl_add_u64 v[18:19], v[18:19], 0, s[40:41]
	s_waitcnt vmcnt(31)
	v_pk_fma_f32 v[4:5], v[116:117], v[26:27], v[4:5] op_sel_hi:[1,0,1]
	v_pk_fma_f32 v[6:7], v[118:119], v[26:27], v[6:7] op_sel_hi:[1,0,1]
	v_pk_fma_f32 v[12:13], v[116:117], v[30:31], v[12:13] op_sel_hi:[1,0,1]
	v_pk_fma_f32 v[14:15], v[118:119], v[30:31], v[14:15] op_sel_hi:[1,0,1]
	v_pk_fma_f32 v[8:9], v[116:117], v[34:35], v[8:9] op_sel_hi:[1,0,1]
	v_pk_fma_f32 v[10:11], v[118:119], v[34:35], v[10:11] op_sel_hi:[1,0,1]
	global_load_dwordx4 v[116:119], v[18:19], off
	v_lshl_add_u64 v[18:19], v[18:19], 0, s[40:41]
	s_waitcnt vmcnt(31)
	v_pk_fma_f32 v[4:5], v[120:121], v[26:27], v[4:5] op_sel:[0,1,0]
	v_pk_fma_f32 v[6:7], v[122:123], v[26:27], v[6:7] op_sel:[0,1,0]
	v_pk_fma_f32 v[12:13], v[120:121], v[30:31], v[12:13] op_sel:[0,1,0]
	v_pk_fma_f32 v[14:15], v[122:123], v[30:31], v[14:15] op_sel:[0,1,0]
	v_pk_fma_f32 v[8:9], v[120:121], v[34:35], v[8:9] op_sel:[0,1,0]
	v_pk_fma_f32 v[10:11], v[122:123], v[34:35], v[10:11] op_sel:[0,1,0]
	global_load_dwordx4 v[120:123], v[18:19], off
	v_lshl_add_u64 v[18:19], v[18:19], 0, s[40:41]
	ds_read_b128 v[24:27], v23 offset:352
	ds_read_b128 v[28:31], v23 offset:4448
	ds_read_b128 v[32:35], v23 offset:8544
	s_waitcnt lgkmcnt(3)
	s_waitcnt vmcnt(31)
	v_pk_fma_f32 v[4:5], v[124:125], v[36:37], v[4:5] op_sel_hi:[1,0,1]
	v_pk_fma_f32 v[6:7], v[126:127], v[36:37], v[6:7] op_sel_hi:[1,0,1]
	v_pk_fma_f32 v[12:13], v[124:125], v[40:41], v[12:13] op_sel_hi:[1,0,1]
	v_pk_fma_f32 v[14:15], v[126:127], v[40:41], v[14:15] op_sel_hi:[1,0,1]
	v_pk_fma_f32 v[8:9], v[124:125], v[0:1], v[8:9] op_sel_hi:[1,0,1]
	v_pk_fma_f32 v[10:11], v[126:127], v[0:1], v[10:11] op_sel_hi:[1,0,1]
	global_load_dwordx4 v[124:127], v[18:19], off
	v_lshl_add_u64 v[18:19], v[18:19], 0, s[40:41]
	s_waitcnt vmcnt(31)
	v_pk_fma_f32 v[4:5], v[136:137], v[36:37], v[4:5] op_sel:[0,1,0]
	v_pk_fma_f32 v[6:7], v[138:139], v[36:37], v[6:7] op_sel:[0,1,0]
	v_pk_fma_f32 v[12:13], v[136:137], v[40:41], v[12:13] op_sel:[0,1,0]
	v_pk_fma_f32 v[14:15], v[138:139], v[40:41], v[14:15] op_sel:[0,1,0]
	v_pk_fma_f32 v[8:9], v[136:137], v[0:1], v[8:9] op_sel:[0,1,0]
	v_pk_fma_f32 v[10:11], v[138:139], v[0:1], v[10:11] op_sel:[0,1,0]
	global_load_dwordx4 v[136:139], v[18:19], off
	v_lshl_add_u64 v[18:19], v[18:19], 0, s[40:41]
	s_waitcnt vmcnt(31)
	v_pk_fma_f32 v[4:5], v[140:141], v[38:39], v[4:5] op_sel_hi:[1,0,1]
	v_pk_fma_f32 v[6:7], v[142:143], v[38:39], v[6:7] op_sel_hi:[1,0,1]
	v_pk_fma_f32 v[12:13], v[140:141], v[42:43], v[12:13] op_sel_hi:[1,0,1]
	v_pk_fma_f32 v[14:15], v[142:143], v[42:43], v[14:15] op_sel_hi:[1,0,1]
	v_pk_fma_f32 v[8:9], v[140:141], v[2:3], v[8:9] op_sel_hi:[1,0,1]
	v_pk_fma_f32 v[10:11], v[142:143], v[2:3], v[10:11] op_sel_hi:[1,0,1]
	global_load_dwordx4 v[140:143], v[18:19], off
	v_lshl_add_u64 v[18:19], v[18:19], 0, s[40:41]
	s_waitcnt vmcnt(31)
	v_pk_fma_f32 v[4:5], v[144:145], v[38:39], v[4:5] op_sel:[0,1,0]
	v_pk_fma_f32 v[6:7], v[146:147], v[38:39], v[6:7] op_sel:[0,1,0]
	v_pk_fma_f32 v[12:13], v[144:145], v[42:43], v[12:13] op_sel:[0,1,0]
	v_pk_fma_f32 v[14:15], v[146:147], v[42:43], v[14:15] op_sel:[0,1,0]
	v_pk_fma_f32 v[8:9], v[144:145], v[2:3], v[8:9] op_sel:[0,1,0]
	v_pk_fma_f32 v[10:11], v[146:147], v[2:3], v[10:11] op_sel:[0,1,0]
	global_load_dwordx4 v[144:147], v[18:19], off
	v_lshl_add_u64 v[18:19], v[18:19], 0, s[40:41]
	ds_read_b128 v[36:39], v23 offset:368
	ds_read_b128 v[40:43], v23 offset:4464
	ds_read_b128 v[0:3], v23 offset:8560
	s_waitcnt lgkmcnt(3)
	s_waitcnt vmcnt(31)
	v_pk_fma_f32 v[4:5], v[148:149], v[24:25], v[4:5] op_sel_hi:[1,0,1]
	v_pk_fma_f32 v[6:7], v[150:151], v[24:25], v[6:7] op_sel_hi:[1,0,1]
	v_pk_fma_f32 v[12:13], v[148:149], v[28:29], v[12:13] op_sel_hi:[1,0,1]
	v_pk_fma_f32 v[14:15], v[150:151], v[28:29], v[14:15] op_sel_hi:[1,0,1]
	v_pk_fma_f32 v[8:9], v[148:149], v[32:33], v[8:9] op_sel_hi:[1,0,1]
	v_pk_fma_f32 v[10:11], v[150:151], v[32:33], v[10:11] op_sel_hi:[1,0,1]
	global_load_dwordx4 v[148:151], v[18:19], off
	v_lshl_add_u64 v[18:19], v[18:19], 0, s[40:41]
	s_waitcnt vmcnt(31)
	v_pk_fma_f32 v[4:5], v[152:153], v[24:25], v[4:5] op_sel:[0,1,0]
	v_pk_fma_f32 v[6:7], v[154:155], v[24:25], v[6:7] op_sel:[0,1,0]
	v_pk_fma_f32 v[12:13], v[152:153], v[28:29], v[12:13] op_sel:[0,1,0]
	v_pk_fma_f32 v[14:15], v[154:155], v[28:29], v[14:15] op_sel:[0,1,0]
	v_pk_fma_f32 v[8:9], v[152:153], v[32:33], v[8:9] op_sel:[0,1,0]
	v_pk_fma_f32 v[10:11], v[154:155], v[32:33], v[10:11] op_sel:[0,1,0]
	global_load_dwordx4 v[152:155], v[18:19], off
	v_lshl_add_u64 v[18:19], v[18:19], 0, s[40:41]
	s_waitcnt vmcnt(31)
	v_pk_fma_f32 v[4:5], v[156:157], v[26:27], v[4:5] op_sel_hi:[1,0,1]
	v_pk_fma_f32 v[6:7], v[158:159], v[26:27], v[6:7] op_sel_hi:[1,0,1]
	v_pk_fma_f32 v[12:13], v[156:157], v[30:31], v[12:13] op_sel_hi:[1,0,1]
	v_pk_fma_f32 v[14:15], v[158:159], v[30:31], v[14:15] op_sel_hi:[1,0,1]
	v_pk_fma_f32 v[8:9], v[156:157], v[34:35], v[8:9] op_sel_hi:[1,0,1]
	v_pk_fma_f32 v[10:11], v[158:159], v[34:35], v[10:11] op_sel_hi:[1,0,1]
	global_load_dwordx4 v[156:159], v[18:19], off
	v_lshl_add_u64 v[18:19], v[18:19], 0, s[40:41]
	s_waitcnt vmcnt(31)
	v_pk_fma_f32 v[4:5], v[160:161], v[26:27], v[4:5] op_sel:[0,1,0]
	v_pk_fma_f32 v[6:7], v[162:163], v[26:27], v[6:7] op_sel:[0,1,0]
	v_pk_fma_f32 v[12:13], v[160:161], v[30:31], v[12:13] op_sel:[0,1,0]
	v_pk_fma_f32 v[14:15], v[162:163], v[30:31], v[14:15] op_sel:[0,1,0]
	v_pk_fma_f32 v[8:9], v[160:161], v[34:35], v[8:9] op_sel:[0,1,0]
	v_pk_fma_f32 v[10:11], v[162:163], v[34:35], v[10:11] op_sel:[0,1,0]
	global_load_dwordx4 v[160:163], v[18:19], off
	v_lshl_add_u64 v[18:19], v[18:19], 0, s[40:41]
	ds_read_b128 v[24:27], v23 offset:384
	ds_read_b128 v[28:31], v23 offset:4480
	ds_read_b128 v[32:35], v23 offset:8576
	s_waitcnt lgkmcnt(3)
	s_waitcnt vmcnt(31)
	v_pk_fma_f32 v[4:5], v[164:165], v[36:37], v[4:5] op_sel_hi:[1,0,1]
	v_pk_fma_f32 v[6:7], v[166:167], v[36:37], v[6:7] op_sel_hi:[1,0,1]
	v_pk_fma_f32 v[12:13], v[164:165], v[40:41], v[12:13] op_sel_hi:[1,0,1]
	v_pk_fma_f32 v[14:15], v[166:167], v[40:41], v[14:15] op_sel_hi:[1,0,1]
	v_pk_fma_f32 v[8:9], v[164:165], v[0:1], v[8:9] op_sel_hi:[1,0,1]
	v_pk_fma_f32 v[10:11], v[166:167], v[0:1], v[10:11] op_sel_hi:[1,0,1]
	global_load_dwordx4 v[164:167], v[18:19], off
	v_lshl_add_u64 v[18:19], v[18:19], 0, s[40:41]
	s_waitcnt vmcnt(31)
	v_pk_fma_f32 v[4:5], v[202:203], v[36:37], v[4:5] op_sel:[0,1,0]
	v_pk_fma_f32 v[6:7], v[204:205], v[36:37], v[6:7] op_sel:[0,1,0]
	v_pk_fma_f32 v[12:13], v[202:203], v[40:41], v[12:13] op_sel:[0,1,0]
	v_pk_fma_f32 v[14:15], v[204:205], v[40:41], v[14:15] op_sel:[0,1,0]
	v_pk_fma_f32 v[8:9], v[202:203], v[0:1], v[8:9] op_sel:[0,1,0]
	v_pk_fma_f32 v[10:11], v[204:205], v[0:1], v[10:11] op_sel:[0,1,0]
	global_load_dwordx4 v[202:205], v[18:19], off
	v_lshl_add_u64 v[18:19], v[18:19], 0, s[40:41]
	s_waitcnt vmcnt(31)
	v_pk_fma_f32 v[4:5], v[206:207], v[38:39], v[4:5] op_sel_hi:[1,0,1]
	v_pk_fma_f32 v[6:7], v[208:209], v[38:39], v[6:7] op_sel_hi:[1,0,1]
	v_pk_fma_f32 v[12:13], v[206:207], v[42:43], v[12:13] op_sel_hi:[1,0,1]
	v_pk_fma_f32 v[14:15], v[208:209], v[42:43], v[14:15] op_sel_hi:[1,0,1]
	v_pk_fma_f32 v[8:9], v[206:207], v[2:3], v[8:9] op_sel_hi:[1,0,1]
	v_pk_fma_f32 v[10:11], v[208:209], v[2:3], v[10:11] op_sel_hi:[1,0,1]
	global_load_dwordx4 v[206:209], v[18:19], off
	v_lshl_add_u64 v[18:19], v[18:19], 0, s[40:41]
	s_waitcnt vmcnt(31)
	v_pk_fma_f32 v[4:5], v[210:211], v[38:39], v[4:5] op_sel:[0,1,0]
	v_pk_fma_f32 v[6:7], v[212:213], v[38:39], v[6:7] op_sel:[0,1,0]
	v_pk_fma_f32 v[12:13], v[210:211], v[42:43], v[12:13] op_sel:[0,1,0]
	v_pk_fma_f32 v[14:15], v[212:213], v[42:43], v[14:15] op_sel:[0,1,0]
	v_pk_fma_f32 v[8:9], v[210:211], v[2:3], v[8:9] op_sel:[0,1,0]
	v_pk_fma_f32 v[10:11], v[212:213], v[2:3], v[10:11] op_sel:[0,1,0]
	global_load_dwordx4 v[210:213], v[18:19], off
	v_lshl_add_u64 v[18:19], v[18:19], 0, s[40:41]
	ds_read_b128 v[36:39], v23 offset:400
	ds_read_b128 v[40:43], v23 offset:4496
	ds_read_b128 v[0:3], v23 offset:8592
	s_waitcnt lgkmcnt(3)
	s_waitcnt vmcnt(31)
	v_pk_fma_f32 v[4:5], v[44:45], v[24:25], v[4:5] op_sel_hi:[1,0,1]
	v_pk_fma_f32 v[6:7], v[46:47], v[24:25], v[6:7] op_sel_hi:[1,0,1]
	v_pk_fma_f32 v[12:13], v[44:45], v[28:29], v[12:13] op_sel_hi:[1,0,1]
	v_pk_fma_f32 v[14:15], v[46:47], v[28:29], v[14:15] op_sel_hi:[1,0,1]
	v_pk_fma_f32 v[8:9], v[44:45], v[32:33], v[8:9] op_sel_hi:[1,0,1]
	v_pk_fma_f32 v[10:11], v[46:47], v[32:33], v[10:11] op_sel_hi:[1,0,1]
	s_waitcnt vmcnt(30)
	v_pk_fma_f32 v[4:5], v[48:49], v[24:25], v[4:5] op_sel:[0,1,0]
	v_pk_fma_f32 v[6:7], v[50:51], v[24:25], v[6:7] op_sel:[0,1,0]
	v_pk_fma_f32 v[12:13], v[48:49], v[28:29], v[12:13] op_sel:[0,1,0]
	v_pk_fma_f32 v[14:15], v[50:51], v[28:29], v[14:15] op_sel:[0,1,0]
	v_pk_fma_f32 v[8:9], v[48:49], v[32:33], v[8:9] op_sel:[0,1,0]
	v_pk_fma_f32 v[10:11], v[50:51], v[32:33], v[10:11] op_sel:[0,1,0]
	s_waitcnt vmcnt(29)
	v_pk_fma_f32 v[4:5], v[52:53], v[26:27], v[4:5] op_sel_hi:[1,0,1]
	v_pk_fma_f32 v[6:7], v[54:55], v[26:27], v[6:7] op_sel_hi:[1,0,1]
	v_pk_fma_f32 v[12:13], v[52:53], v[30:31], v[12:13] op_sel_hi:[1,0,1]
	v_pk_fma_f32 v[14:15], v[54:55], v[30:31], v[14:15] op_sel_hi:[1,0,1]
	v_pk_fma_f32 v[8:9], v[52:53], v[34:35], v[8:9] op_sel_hi:[1,0,1]
	v_pk_fma_f32 v[10:11], v[54:55], v[34:35], v[10:11] op_sel_hi:[1,0,1]
	s_waitcnt vmcnt(28)
	v_pk_fma_f32 v[4:5], v[56:57], v[26:27], v[4:5] op_sel:[0,1,0]
	v_pk_fma_f32 v[6:7], v[58:59], v[26:27], v[6:7] op_sel:[0,1,0]
	v_pk_fma_f32 v[12:13], v[56:57], v[30:31], v[12:13] op_sel:[0,1,0]
	v_pk_fma_f32 v[14:15], v[58:59], v[30:31], v[14:15] op_sel:[0,1,0]
	v_pk_fma_f32 v[8:9], v[56:57], v[34:35], v[8:9] op_sel:[0,1,0]
	v_pk_fma_f32 v[10:11], v[58:59], v[34:35], v[10:11] op_sel:[0,1,0]
	ds_read_b128 v[24:27], v23 offset:416
	ds_read_b128 v[28:31], v23 offset:4512
	ds_read_b128 v[32:35], v23 offset:8608
	s_waitcnt lgkmcnt(3)
	s_waitcnt vmcnt(27)
	v_pk_fma_f32 v[4:5], v[60:61], v[36:37], v[4:5] op_sel_hi:[1,0,1]
	v_pk_fma_f32 v[6:7], v[62:63], v[36:37], v[6:7] op_sel_hi:[1,0,1]
	v_pk_fma_f32 v[12:13], v[60:61], v[40:41], v[12:13] op_sel_hi:[1,0,1]
	v_pk_fma_f32 v[14:15], v[62:63], v[40:41], v[14:15] op_sel_hi:[1,0,1]
	v_pk_fma_f32 v[8:9], v[60:61], v[0:1], v[8:9] op_sel_hi:[1,0,1]
	v_pk_fma_f32 v[10:11], v[62:63], v[0:1], v[10:11] op_sel_hi:[1,0,1]
	s_waitcnt vmcnt(26)
	v_pk_fma_f32 v[4:5], v[64:65], v[36:37], v[4:5] op_sel:[0,1,0]
	v_pk_fma_f32 v[6:7], v[66:67], v[36:37], v[6:7] op_sel:[0,1,0]
	v_pk_fma_f32 v[12:13], v[64:65], v[40:41], v[12:13] op_sel:[0,1,0]
	v_pk_fma_f32 v[14:15], v[66:67], v[40:41], v[14:15] op_sel:[0,1,0]
	v_pk_fma_f32 v[8:9], v[64:65], v[0:1], v[8:9] op_sel:[0,1,0]
	v_pk_fma_f32 v[10:11], v[66:67], v[0:1], v[10:11] op_sel:[0,1,0]
	s_waitcnt vmcnt(25)
	v_pk_fma_f32 v[4:5], v[68:69], v[38:39], v[4:5] op_sel_hi:[1,0,1]
	v_pk_fma_f32 v[6:7], v[70:71], v[38:39], v[6:7] op_sel_hi:[1,0,1]
	v_pk_fma_f32 v[12:13], v[68:69], v[42:43], v[12:13] op_sel_hi:[1,0,1]
	v_pk_fma_f32 v[14:15], v[70:71], v[42:43], v[14:15] op_sel_hi:[1,0,1]
	v_pk_fma_f32 v[8:9], v[68:69], v[2:3], v[8:9] op_sel_hi:[1,0,1]
	v_pk_fma_f32 v[10:11], v[70:71], v[2:3], v[10:11] op_sel_hi:[1,0,1]
	s_waitcnt vmcnt(24)
	v_pk_fma_f32 v[4:5], v[72:73], v[38:39], v[4:5] op_sel:[0,1,0]
	v_pk_fma_f32 v[6:7], v[74:75], v[38:39], v[6:7] op_sel:[0,1,0]
	v_pk_fma_f32 v[12:13], v[72:73], v[42:43], v[12:13] op_sel:[0,1,0]
	v_pk_fma_f32 v[14:15], v[74:75], v[42:43], v[14:15] op_sel:[0,1,0]
	v_pk_fma_f32 v[8:9], v[72:73], v[2:3], v[8:9] op_sel:[0,1,0]
	v_pk_fma_f32 v[10:11], v[74:75], v[2:3], v[10:11] op_sel:[0,1,0]
	ds_read_b128 v[36:39], v23 offset:432
	ds_read_b128 v[40:43], v23 offset:4528
	ds_read_b128 v[0:3], v23 offset:8624
	s_waitcnt lgkmcnt(3)
	s_waitcnt vmcnt(23)
	v_pk_fma_f32 v[4:5], v[76:77], v[24:25], v[4:5] op_sel_hi:[1,0,1]
	v_pk_fma_f32 v[6:7], v[78:79], v[24:25], v[6:7] op_sel_hi:[1,0,1]
	v_pk_fma_f32 v[12:13], v[76:77], v[28:29], v[12:13] op_sel_hi:[1,0,1]
	v_pk_fma_f32 v[14:15], v[78:79], v[28:29], v[14:15] op_sel_hi:[1,0,1]
	v_pk_fma_f32 v[8:9], v[76:77], v[32:33], v[8:9] op_sel_hi:[1,0,1]
	v_pk_fma_f32 v[10:11], v[78:79], v[32:33], v[10:11] op_sel_hi:[1,0,1]
	s_waitcnt vmcnt(22)
	v_pk_fma_f32 v[4:5], v[80:81], v[24:25], v[4:5] op_sel:[0,1,0]
	v_pk_fma_f32 v[6:7], v[82:83], v[24:25], v[6:7] op_sel:[0,1,0]
	v_pk_fma_f32 v[12:13], v[80:81], v[28:29], v[12:13] op_sel:[0,1,0]
	v_pk_fma_f32 v[14:15], v[82:83], v[28:29], v[14:15] op_sel:[0,1,0]
	v_pk_fma_f32 v[8:9], v[80:81], v[32:33], v[8:9] op_sel:[0,1,0]
	v_pk_fma_f32 v[10:11], v[82:83], v[32:33], v[10:11] op_sel:[0,1,0]
	s_waitcnt vmcnt(21)
	v_pk_fma_f32 v[4:5], v[84:85], v[26:27], v[4:5] op_sel_hi:[1,0,1]
	v_pk_fma_f32 v[6:7], v[86:87], v[26:27], v[6:7] op_sel_hi:[1,0,1]
	v_pk_fma_f32 v[12:13], v[84:85], v[30:31], v[12:13] op_sel_hi:[1,0,1]
	v_pk_fma_f32 v[14:15], v[86:87], v[30:31], v[14:15] op_sel_hi:[1,0,1]
	v_pk_fma_f32 v[8:9], v[84:85], v[34:35], v[8:9] op_sel_hi:[1,0,1]
	v_pk_fma_f32 v[10:11], v[86:87], v[34:35], v[10:11] op_sel_hi:[1,0,1]
	s_waitcnt vmcnt(20)
	v_pk_fma_f32 v[4:5], v[88:89], v[26:27], v[4:5] op_sel:[0,1,0]
	v_pk_fma_f32 v[6:7], v[90:91], v[26:27], v[6:7] op_sel:[0,1,0]
	v_pk_fma_f32 v[12:13], v[88:89], v[30:31], v[12:13] op_sel:[0,1,0]
	v_pk_fma_f32 v[14:15], v[90:91], v[30:31], v[14:15] op_sel:[0,1,0]
	v_pk_fma_f32 v[8:9], v[88:89], v[34:35], v[8:9] op_sel:[0,1,0]
	v_pk_fma_f32 v[10:11], v[90:91], v[34:35], v[10:11] op_sel:[0,1,0]
	ds_read_b128 v[24:27], v23 offset:448
	ds_read_b128 v[28:31], v23 offset:4544
	ds_read_b128 v[32:35], v23 offset:8640
	s_waitcnt lgkmcnt(3)
	s_waitcnt vmcnt(19)
	v_pk_fma_f32 v[4:5], v[92:93], v[36:37], v[4:5] op_sel_hi:[1,0,1]
	v_pk_fma_f32 v[6:7], v[94:95], v[36:37], v[6:7] op_sel_hi:[1,0,1]
	v_pk_fma_f32 v[12:13], v[92:93], v[40:41], v[12:13] op_sel_hi:[1,0,1]
	v_pk_fma_f32 v[14:15], v[94:95], v[40:41], v[14:15] op_sel_hi:[1,0,1]
	v_pk_fma_f32 v[8:9], v[92:93], v[0:1], v[8:9] op_sel_hi:[1,0,1]
	v_pk_fma_f32 v[10:11], v[94:95], v[0:1], v[10:11] op_sel_hi:[1,0,1]
	s_waitcnt vmcnt(18)
	v_pk_fma_f32 v[4:5], v[96:97], v[36:37], v[4:5] op_sel:[0,1,0]
	v_pk_fma_f32 v[6:7], v[98:99], v[36:37], v[6:7] op_sel:[0,1,0]
	v_pk_fma_f32 v[12:13], v[96:97], v[40:41], v[12:13] op_sel:[0,1,0]
	v_pk_fma_f32 v[14:15], v[98:99], v[40:41], v[14:15] op_sel:[0,1,0]
	v_pk_fma_f32 v[8:9], v[96:97], v[0:1], v[8:9] op_sel:[0,1,0]
	v_pk_fma_f32 v[10:11], v[98:99], v[0:1], v[10:11] op_sel:[0,1,0]
	s_waitcnt vmcnt(17)
	v_pk_fma_f32 v[4:5], v[100:101], v[38:39], v[4:5] op_sel_hi:[1,0,1]
	v_pk_fma_f32 v[6:7], v[102:103], v[38:39], v[6:7] op_sel_hi:[1,0,1]
	v_pk_fma_f32 v[12:13], v[100:101], v[42:43], v[12:13] op_sel_hi:[1,0,1]
	v_pk_fma_f32 v[14:15], v[102:103], v[42:43], v[14:15] op_sel_hi:[1,0,1]
	v_pk_fma_f32 v[8:9], v[100:101], v[2:3], v[8:9] op_sel_hi:[1,0,1]
	v_pk_fma_f32 v[10:11], v[102:103], v[2:3], v[10:11] op_sel_hi:[1,0,1]
	s_waitcnt vmcnt(16)
	v_pk_fma_f32 v[4:5], v[104:105], v[38:39], v[4:5] op_sel:[0,1,0]
	v_pk_fma_f32 v[6:7], v[106:107], v[38:39], v[6:7] op_sel:[0,1,0]
	v_pk_fma_f32 v[12:13], v[104:105], v[42:43], v[12:13] op_sel:[0,1,0]
	v_pk_fma_f32 v[14:15], v[106:107], v[42:43], v[14:15] op_sel:[0,1,0]
	v_pk_fma_f32 v[8:9], v[104:105], v[2:3], v[8:9] op_sel:[0,1,0]
	v_pk_fma_f32 v[10:11], v[106:107], v[2:3], v[10:11] op_sel:[0,1,0]
	ds_read_b128 v[36:39], v23 offset:464
	ds_read_b128 v[40:43], v23 offset:4560
	ds_read_b128 v[0:3], v23 offset:8656
	s_waitcnt lgkmcnt(3)
	s_waitcnt vmcnt(15)
	v_pk_fma_f32 v[4:5], v[108:109], v[24:25], v[4:5] op_sel_hi:[1,0,1]
	v_pk_fma_f32 v[6:7], v[110:111], v[24:25], v[6:7] op_sel_hi:[1,0,1]
	v_pk_fma_f32 v[12:13], v[108:109], v[28:29], v[12:13] op_sel_hi:[1,0,1]
	v_pk_fma_f32 v[14:15], v[110:111], v[28:29], v[14:15] op_sel_hi:[1,0,1]
	v_pk_fma_f32 v[8:9], v[108:109], v[32:33], v[8:9] op_sel_hi:[1,0,1]
	v_pk_fma_f32 v[10:11], v[110:111], v[32:33], v[10:11] op_sel_hi:[1,0,1]
	s_waitcnt vmcnt(14)
	v_pk_fma_f32 v[4:5], v[112:113], v[24:25], v[4:5] op_sel:[0,1,0]
	v_pk_fma_f32 v[6:7], v[114:115], v[24:25], v[6:7] op_sel:[0,1,0]
	v_pk_fma_f32 v[12:13], v[112:113], v[28:29], v[12:13] op_sel:[0,1,0]
	v_pk_fma_f32 v[14:15], v[114:115], v[28:29], v[14:15] op_sel:[0,1,0]
	v_pk_fma_f32 v[8:9], v[112:113], v[32:33], v[8:9] op_sel:[0,1,0]
	v_pk_fma_f32 v[10:11], v[114:115], v[32:33], v[10:11] op_sel:[0,1,0]
	s_waitcnt vmcnt(13)
	v_pk_fma_f32 v[4:5], v[116:117], v[26:27], v[4:5] op_sel_hi:[1,0,1]
	v_pk_fma_f32 v[6:7], v[118:119], v[26:27], v[6:7] op_sel_hi:[1,0,1]
	v_pk_fma_f32 v[12:13], v[116:117], v[30:31], v[12:13] op_sel_hi:[1,0,1]
	v_pk_fma_f32 v[14:15], v[118:119], v[30:31], v[14:15] op_sel_hi:[1,0,1]
	v_pk_fma_f32 v[8:9], v[116:117], v[34:35], v[8:9] op_sel_hi:[1,0,1]
	v_pk_fma_f32 v[10:11], v[118:119], v[34:35], v[10:11] op_sel_hi:[1,0,1]
	s_waitcnt vmcnt(12)
	v_pk_fma_f32 v[4:5], v[120:121], v[26:27], v[4:5] op_sel:[0,1,0]
	v_pk_fma_f32 v[6:7], v[122:123], v[26:27], v[6:7] op_sel:[0,1,0]
	v_pk_fma_f32 v[12:13], v[120:121], v[30:31], v[12:13] op_sel:[0,1,0]
	v_pk_fma_f32 v[14:15], v[122:123], v[30:31], v[14:15] op_sel:[0,1,0]
	v_pk_fma_f32 v[8:9], v[120:121], v[34:35], v[8:9] op_sel:[0,1,0]
	v_pk_fma_f32 v[10:11], v[122:123], v[34:35], v[10:11] op_sel:[0,1,0]
	ds_read_b128 v[24:27], v23 offset:480
	ds_read_b128 v[28:31], v23 offset:4576
	ds_read_b128 v[32:35], v23 offset:8672
	s_waitcnt lgkmcnt(3)
	s_waitcnt vmcnt(11)
	v_pk_fma_f32 v[4:5], v[124:125], v[36:37], v[4:5] op_sel_hi:[1,0,1]
	v_pk_fma_f32 v[6:7], v[126:127], v[36:37], v[6:7] op_sel_hi:[1,0,1]
	v_pk_fma_f32 v[12:13], v[124:125], v[40:41], v[12:13] op_sel_hi:[1,0,1]
	v_pk_fma_f32 v[14:15], v[126:127], v[40:41], v[14:15] op_sel_hi:[1,0,1]
	v_pk_fma_f32 v[8:9], v[124:125], v[0:1], v[8:9] op_sel_hi:[1,0,1]
	v_pk_fma_f32 v[10:11], v[126:127], v[0:1], v[10:11] op_sel_hi:[1,0,1]
	s_waitcnt vmcnt(10)
	v_pk_fma_f32 v[4:5], v[136:137], v[36:37], v[4:5] op_sel:[0,1,0]
	v_pk_fma_f32 v[6:7], v[138:139], v[36:37], v[6:7] op_sel:[0,1,0]
	v_pk_fma_f32 v[12:13], v[136:137], v[40:41], v[12:13] op_sel:[0,1,0]
	v_pk_fma_f32 v[14:15], v[138:139], v[40:41], v[14:15] op_sel:[0,1,0]
	v_pk_fma_f32 v[8:9], v[136:137], v[0:1], v[8:9] op_sel:[0,1,0]
	v_pk_fma_f32 v[10:11], v[138:139], v[0:1], v[10:11] op_sel:[0,1,0]
	s_waitcnt vmcnt(9)
	v_pk_fma_f32 v[4:5], v[140:141], v[38:39], v[4:5] op_sel_hi:[1,0,1]
	v_pk_fma_f32 v[6:7], v[142:143], v[38:39], v[6:7] op_sel_hi:[1,0,1]
	v_pk_fma_f32 v[12:13], v[140:141], v[42:43], v[12:13] op_sel_hi:[1,0,1]
	v_pk_fma_f32 v[14:15], v[142:143], v[42:43], v[14:15] op_sel_hi:[1,0,1]
	v_pk_fma_f32 v[8:9], v[140:141], v[2:3], v[8:9] op_sel_hi:[1,0,1]
	v_pk_fma_f32 v[10:11], v[142:143], v[2:3], v[10:11] op_sel_hi:[1,0,1]
	s_waitcnt vmcnt(8)
	v_pk_fma_f32 v[4:5], v[144:145], v[38:39], v[4:5] op_sel:[0,1,0]
	v_pk_fma_f32 v[6:7], v[146:147], v[38:39], v[6:7] op_sel:[0,1,0]
	v_pk_fma_f32 v[12:13], v[144:145], v[42:43], v[12:13] op_sel:[0,1,0]
	v_pk_fma_f32 v[14:15], v[146:147], v[42:43], v[14:15] op_sel:[0,1,0]
	v_pk_fma_f32 v[8:9], v[144:145], v[2:3], v[8:9] op_sel:[0,1,0]
	v_pk_fma_f32 v[10:11], v[146:147], v[2:3], v[10:11] op_sel:[0,1,0]
	ds_read_b128 v[36:39], v23 offset:496
	ds_read_b128 v[40:43], v23 offset:4592
	ds_read_b128 v[0:3], v23 offset:8688
	s_waitcnt lgkmcnt(3)
	s_waitcnt vmcnt(7)
	v_pk_fma_f32 v[4:5], v[148:149], v[24:25], v[4:5] op_sel_hi:[1,0,1]
	v_pk_fma_f32 v[6:7], v[150:151], v[24:25], v[6:7] op_sel_hi:[1,0,1]
	v_pk_fma_f32 v[12:13], v[148:149], v[28:29], v[12:13] op_sel_hi:[1,0,1]
	v_pk_fma_f32 v[14:15], v[150:151], v[28:29], v[14:15] op_sel_hi:[1,0,1]
	v_pk_fma_f32 v[8:9], v[148:149], v[32:33], v[8:9] op_sel_hi:[1,0,1]
	v_pk_fma_f32 v[10:11], v[150:151], v[32:33], v[10:11] op_sel_hi:[1,0,1]
	s_waitcnt vmcnt(6)
	v_pk_fma_f32 v[4:5], v[152:153], v[24:25], v[4:5] op_sel:[0,1,0]
	v_pk_fma_f32 v[6:7], v[154:155], v[24:25], v[6:7] op_sel:[0,1,0]
	v_pk_fma_f32 v[12:13], v[152:153], v[28:29], v[12:13] op_sel:[0,1,0]
	v_pk_fma_f32 v[14:15], v[154:155], v[28:29], v[14:15] op_sel:[0,1,0]
	v_pk_fma_f32 v[8:9], v[152:153], v[32:33], v[8:9] op_sel:[0,1,0]
	v_pk_fma_f32 v[10:11], v[154:155], v[32:33], v[10:11] op_sel:[0,1,0]
	s_waitcnt vmcnt(5)
	v_pk_fma_f32 v[4:5], v[156:157], v[26:27], v[4:5] op_sel_hi:[1,0,1]
	v_pk_fma_f32 v[6:7], v[158:159], v[26:27], v[6:7] op_sel_hi:[1,0,1]
	v_pk_fma_f32 v[12:13], v[156:157], v[30:31], v[12:13] op_sel_hi:[1,0,1]
	v_pk_fma_f32 v[14:15], v[158:159], v[30:31], v[14:15] op_sel_hi:[1,0,1]
	v_pk_fma_f32 v[8:9], v[156:157], v[34:35], v[8:9] op_sel_hi:[1,0,1]
	v_pk_fma_f32 v[10:11], v[158:159], v[34:35], v[10:11] op_sel_hi:[1,0,1]
	s_waitcnt vmcnt(4)
	v_pk_fma_f32 v[4:5], v[160:161], v[26:27], v[4:5] op_sel:[0,1,0]
	v_pk_fma_f32 v[6:7], v[162:163], v[26:27], v[6:7] op_sel:[0,1,0]
	v_pk_fma_f32 v[12:13], v[160:161], v[30:31], v[12:13] op_sel:[0,1,0]
	v_pk_fma_f32 v[14:15], v[162:163], v[30:31], v[14:15] op_sel:[0,1,0]
	v_pk_fma_f32 v[8:9], v[160:161], v[34:35], v[8:9] op_sel:[0,1,0]
	v_pk_fma_f32 v[10:11], v[162:163], v[34:35], v[10:11] op_sel:[0,1,0]
	s_waitcnt lgkmcnt(0)
	s_waitcnt vmcnt(3)
	v_pk_fma_f32 v[4:5], v[164:165], v[36:37], v[4:5] op_sel_hi:[1,0,1]
	v_pk_fma_f32 v[6:7], v[166:167], v[36:37], v[6:7] op_sel_hi:[1,0,1]
	v_pk_fma_f32 v[12:13], v[164:165], v[40:41], v[12:13] op_sel_hi:[1,0,1]
	v_pk_fma_f32 v[14:15], v[166:167], v[40:41], v[14:15] op_sel_hi:[1,0,1]
	v_pk_fma_f32 v[8:9], v[164:165], v[0:1], v[8:9] op_sel_hi:[1,0,1]
	v_pk_fma_f32 v[10:11], v[166:167], v[0:1], v[10:11] op_sel_hi:[1,0,1]
	s_waitcnt vmcnt(2)
	v_pk_fma_f32 v[4:5], v[202:203], v[36:37], v[4:5] op_sel:[0,1,0]
	v_pk_fma_f32 v[6:7], v[204:205], v[36:37], v[6:7] op_sel:[0,1,0]
	v_pk_fma_f32 v[12:13], v[202:203], v[40:41], v[12:13] op_sel:[0,1,0]
	v_pk_fma_f32 v[14:15], v[204:205], v[40:41], v[14:15] op_sel:[0,1,0]
	v_pk_fma_f32 v[8:9], v[202:203], v[0:1], v[8:9] op_sel:[0,1,0]
	v_pk_fma_f32 v[10:11], v[204:205], v[0:1], v[10:11] op_sel:[0,1,0]
	s_waitcnt vmcnt(1)
	v_pk_fma_f32 v[4:5], v[206:207], v[38:39], v[4:5] op_sel_hi:[1,0,1]
	v_pk_fma_f32 v[6:7], v[208:209], v[38:39], v[6:7] op_sel_hi:[1,0,1]
	v_pk_fma_f32 v[12:13], v[206:207], v[42:43], v[12:13] op_sel_hi:[1,0,1]
	v_pk_fma_f32 v[14:15], v[208:209], v[42:43], v[14:15] op_sel_hi:[1,0,1]
	v_pk_fma_f32 v[8:9], v[206:207], v[2:3], v[8:9] op_sel_hi:[1,0,1]
	v_pk_fma_f32 v[10:11], v[208:209], v[2:3], v[10:11] op_sel_hi:[1,0,1]
	s_waitcnt vmcnt(0)
	v_pk_fma_f32 v[4:5], v[210:211], v[38:39], v[4:5] op_sel:[0,1,0]
	v_pk_fma_f32 v[6:7], v[212:213], v[38:39], v[6:7] op_sel:[0,1,0]
	v_pk_fma_f32 v[12:13], v[210:211], v[42:43], v[12:13] op_sel:[0,1,0]
	v_pk_fma_f32 v[14:15], v[212:213], v[42:43], v[14:15] op_sel:[0,1,0]
	v_pk_fma_f32 v[8:9], v[210:211], v[2:3], v[8:9] op_sel:[0,1,0]
	v_pk_fma_f32 v[10:11], v[212:213], v[2:3], v[10:11] op_sel:[0,1,0]
	s_movk_i32 s4, 0x600
	v_mul_lo_u32 v0, v21, s4
	v_lshl_or_b32 v0, v22, 2, v0
	v_cmp_gt_i32_e32 vcc, s75, v20
	ds_write_b128 v0, v[4:7] offset:12288
	ds_write_b128 v0, v[12:15] offset:12800
	ds_write_b128 v0, v[8:11] offset:13312
	s_waitcnt lgkmcnt(0)
	s_barrier
	s_and_saveexec_b64 s[40:41], vcc
	s_movk_i32 s56, 0x7f
	s_cbranch_execz .LBB0_1360
	v_readlane_b32 s4, v237, 19
	v_and_b32_e32 v0, 0x7f, v20
	s_mul_i32 s37, s34, 0x9000
	v_readlane_b32 s8, v237, 23
	v_lshlrev_b32_e32 v4, 2, v0
	v_or_b32_e32 v0, s36, v0
	s_mul_hi_i32 s35, s34, 0x9000
	v_readlane_b32 s9, v237, 24
	s_add_u32 s54, s8, s37
	v_ashrrev_i32_e32 v1, 31, v0
	s_addc_u32 s55, s9, s35
	v_lshlrev_b64 v[2:3], 2, v[0:1]
	s_mul_hi_i32 s35, s34, 3
	s_mul_i32 s34, s34, 3
	v_lshl_add_u64 v[0:1], s[54:55], 0, v[2:3]
	v_lshl_add_u64 v[2:3], s[46:47], 0, v[2:3]
	s_mov_b64 s[36:37], 0
	v_readlane_b32 s5, v237, 20
	v_readlane_b32 s6, v237, 21
	v_readlane_b32 s7, v237, 22
	v_readlane_b32 s10, v237, 25
	v_readlane_b32 s11, v237, 26
	v_readlane_b32 s12, v237, 27
	v_readlane_b32 s13, v237, 28
	v_readlane_b32 s14, v237, 29
	v_readlane_b32 s15, v237, 30
	v_readlane_b32 s16, v237, 31
	v_readlane_b32 s17, v237, 32
	v_readlane_b32 s18, v237, 33
	v_readlane_b32 s19, v237, 34

.LBB0_1374:
	s_mov_b64 s[60:61], s[90:91]
	v_readlane_b32 s67, v235, 23
	v_readlane_b32 s66, v235, 24
	v_and_b32_e32 v102, 63, v170
	v_and_b32_e32 v99, 7, v102
	v_lshlrev_b32_e32 v96, 3, v99
	v_lshlrev_b32_e32 v99, 4, v99
	v_lshrrev_b32_e32 v98, 3, v102
	v_lshlrev_b32_e32 v97, 4, v98
	v_lshlrev_b32_e32 v98, 2, v98
	v_lshrrev_b32_e32 v102, 6, v170
	s_nop 0
	v_readfirstlane_b32 s6, v102
	v_readlane_b32 s4, v235, 34
	v_readlane_b32 s5, v235, 35
	s_mov_b64 s[34:35], exec
	s_mov_b64 exec, 1
	v_readlane_b32 s17, v237, 0
	s_and_b32 s17, s17, 7
	s_lshl_b32 s17, s17, 8
	s_add_u32 s17, s17, 0x40e0
	v_mov_b32_e32 v104, s17
	v_mov_b32_e32 v105, 1
	s_nop 1
	global_atomic_add v103, v104, v105, s[4:5] sc0
	s_mov_b64 exec, s[34:35]
	s_waitcnt vmcnt(0)
	v_readfirstlane_b32 s6, v103
	s_cmp_ge_u32 s6, 1336
	s_cbranch_scc1 .Lcv_done
	v_readlane_b32 s17, v237, 0
	s_and_b32 s17, s17, 7
	s_mul_i32 s17, s17, 1336
	s_add_u32 s6, s6, s17
	s_lshl_b32 s6, s6, 2
	s_mov_b32 s41, 0
	s_cmp_ge_u32 s6, 22528
	s_cbranch_scc1 .Lcv_t1_1
	s_mul_hi_u32 s4, s6, 1525202
	s_mul_i32 s5, s4, 2816
	s_sub_u32 s17, s6, s5
	s_mul_hi_u32 s34, s17, 24403224
	s_mul_i32 s5, s34, 176
	s_sub_u32 s35, s17, s5
	s_lshl_b32 s40, s35, 5
	s_cmp_ge_u32 s40, 2816
	s_cselect_b32 s5, 1, 0
	s_mul_i32 s17, s5, 2816
	s_sub_u32 s40, s40, s17
	s_lshl_b32 s5, s5, 5
	s_lshr_b32 s17, s40, 6
	s_lshl_b32 s17, s17, 7
	s_add_u32 s5, s5, s17
	s_bfe_u32 s17, s40, 0x10005
	s_lshl_b32 s17, s17, 6
	s_add_u32 s40, s5, s17
	v_readlane_b32 s8, v237, 29
	v_readlane_b32 s9, v237, 30
	s_mul_i32 s5, s4, 0x1600000
	s_mul_i32 s17, s34, 0x160000
	s_add_u32 s5, s5, s17
	s_lshl_b32 s17, s35, 7
	s_add_u32 s5, s5, s17
	s_add_u32 s8, s8, s5
	s_addc_u32 s9, s9, 0
	s_movk_i32 s16, 0x5800
	v_readlane_b32 s10, v235, 34
	v_readlane_b32 s11, v235, 35
	s_mul_i32 s5, s4, 0xbb0000
	s_mul_i32 s17, s40, 0x880
	s_add_u32 s5, s5, s17
	s_lshl_b32 s17, s34, 7
	s_add_u32 s5, s5, s17
	s_add_u32 s5, s5, 0x8000
	s_add_u32 s10, s10, s5
	s_addc_u32 s11, s11, 0
	s_lshl_b32 s41, s41, 31
	s_or_b32 s12, s41, 0x880
	s_branch .Lcv_dec1
.Lcv_t1_1:
	s_cmp_ge_u32 s6, 33792
	s_cbranch_scc1 .Lcv_t2_1
	s_sub_u32 s17, s6, 22528
	s_mul_hi_u32 s4, s17, 3050403
	s_mul_i32 s5, s4, 1408
	s_sub_u32 s17, s17, s5
	s_lshr_b32 s34, s17, 5
	s_and_b32 s35, s17, 31
	s_lshl_b32 s40, s35, 5
	v_readlane_b32 s8, v237, 31
	v_readlane_b32 s9, v237, 32
	s_mul_i32 s5, s4, 0xb00000
	s_mul_i32 s17, s34, 0x40000
	s_add_u32 s5, s5, s17
	s_lshl_b32 s17, s35, 7
	s_add_u32 s5, s5, s17
	s_add_u32 s8, s8, s5
	s_addc_u32 s9, s9, 0
	s_movk_i32 s16, 0x1000
	v_readlane_b32 s10, v235, 34
	v_readlane_b32 s11, v235, 35
	s_mul_i32 s5, s4, 0x5a0000
	s_mul_i32 s17, s40, 0x1680
	s_add_u32 s5, s5, s17
	s_lshl_b32 s17, s34, 7
	s_add_u32 s5, s5, s17
	s_add_u32 s5, s5, 0x5d88000
	s_add_u32 s10, s10, s5
	s_addc_u32 s11, s11, 0
	s_lshl_b32 s41, s41, 31
	s_or_b32 s12, s41, 0x1680
	s_branch .Lcv_dec1
.Lcv_t2_1:
	s_cmp_ge_u32 s6, 40704
	s_cbranch_scc1 .Lcv_t3_1
	s_sub_u32 s17, s6, 33792
	s_mul_hi_u32 s4, s17, 2485514
	s_mul_i32 s5, s4, 1728
	s_sub_u32 s17, s17, s5
	s_mul_hi_u32 s34, s17, 39768216
	s_mul_i32 s5, s34, 108
	s_sub_u32 s35, s17, s5
	s_lshl_b32 s40, s35, 5
	s_cmp_ge_u32 s35, 105
	s_cselect_b32 s41, 1, 0
	s_cselect_b32 s35, 104, s35
	v_readlane_b32 s8, v237, 33
	v_readlane_b32 s9, v237, 34
	s_mul_i32 s5, s4, 0xd20000
	s_mul_i32 s17, s34, 0xd2000
	s_add_u32 s5, s5, s17
	s_lshl_b32 s17, s35, 7
	s_add_u32 s5, s5, s17
	s_add_u32 s8, s8, s5
	s_addc_u32 s9, s9, 0
	s_movk_i32 s16, 0x3480
	v_readlane_b32 s10, v235, 34
	v_readlane_b32 s11, v235, 35
	s_mul_i32 s5, s4, 0x72c000
	s_mul_i32 s17, s40, 0x880
	s_add_u32 s5, s5, s17
	s_lshl_b32 s17, s34, 7
	s_add_u32 s5, s5, s17
	s_add_u32 s5, s5, 0x8a88000
	s_add_u32 s10, s10, s5
	s_addc_u32 s11, s11, 0
	s_lshl_b32 s41, s41, 31
	s_or_b32 s12, s41, 0x880
	s_branch .Lcv_dec1
.Lcv_t3_1:
	s_sub_u32 s17, s6, 40704
	s_lshr_b32 s4, s17, 9
	s_and_b32 s17, s17, 511
	s_lshr_b32 s34, s17, 5
	s_and_b32 s35, s17, 31
	s_lshl_b32 s40, s35, 5
	v_readlane_b32 s8, v237, 35
	v_readlane_b32 s9, v237, 36
	s_mul_i32 s5, s4, 0x400000
	s_mul_i32 s17, s34, 0x40000
	s_add_u32 s5, s5, s17
	s_lshl_b32 s17, s35, 7
	s_add_u32 s5, s5, s17
	s_add_u32 s8, s8, s5
	s_addc_u32 s9, s9, 0
	s_movk_i32 s16, 0x1000
	v_readlane_b32 s10, v235, 34
	v_readlane_b32 s11, v235, 35
	s_mul_i32 s5, s4, 0x220000
	s_mul_i32 s17, s40, 0x880
	s_add_u32 s5, s5, s17
	s_lshl_b32 s17, s34, 7
	s_add_u32 s5, s5, s17
	s_add_u32 s5, s5, 0xa738000
	s_add_u32 s10, s10, s5
	s_addc_u32 s11, s11, 0
	s_lshl_b32 s41, s41, 31
	s_or_b32 s12, s41, 0x880
	s_branch .Lcv_dec1
.Lcv_dec1:
	v_mad_u32_u24 v100, v96, s16, v97
	global_load_dwordx4 v[0:3], v100, s[8:9]
	s_add_u32 s8, s8, s16
	s_addc_u32 s9, s9, 0
	global_load_dwordx4 v[4:7], v100, s[8:9]
	s_add_u32 s8, s8, s16
	s_addc_u32 s9, s9, 0
	global_load_dwordx4 v[8:11], v100, s[8:9]
	s_add_u32 s8, s8, s16
	s_addc_u32 s9, s9, 0
	global_load_dwordx4 v[12:15], v100, s[8:9]
	s_add_u32 s8, s8, s16
	s_addc_u32 s9, s9, 0
	global_load_dwordx4 v[16:19], v100, s[8:9]
	s_add_u32 s8, s8, s16
	s_addc_u32 s9, s9, 0
	global_load_dwordx4 v[20:23], v100, s[8:9]
	s_add_u32 s8, s8, s16
	s_addc_u32 s9, s9, 0
	global_load_dwordx4 v[24:27], v100, s[8:9]
	s_add_u32 s8, s8, s16
	s_addc_u32 s9, s9, 0
	global_load_dwordx4 v[28:31], v100, s[8:9]
	s_mov_b32 s19, 1
.Lcv_loop:
	s_and_b32 s18, s6, 3
	s_cmp_lg_u32 s18, 0
	s_cbranch_scc1 .Lcv_noask_a
	v_readlane_b32 s4, v235, 34
	v_readlane_b32 s5, v235, 35
	s_mov_b64 s[34:35], exec
	s_mov_b64 exec, 1
	v_readlane_b32 s17, v237, 0
	s_and_b32 s17, s17, 7
	s_lshl_b32 s17, s17, 8
	s_add_u32 s17, s17, 0x40e0
	v_mov_b32_e32 v104, s17
	v_mov_b32_e32 v105, 1
	s_nop 1
	global_atomic_add v103, v104, v105, s[4:5] sc0
	s_mov_b64 exec, s[34:35]
.Lcv_noask_a:
	s_and_b32 s18, s6, 3
	s_cmp_eq_u32 s18, 3
	s_cbranch_scc1 .Lcv_chunkend_a
	s_add_u32 s18, s6, 1
	s_branch .Lcv_next_a
.Lcv_chunkend_a:
	v_readfirstlane_b32 s18, v103
	s_cmp_lt_u32 s18, 1336
	s_cbranch_scc0 .Lcv_nonext_a
	v_readlane_b32 s17, v237, 0
	s_and_b32 s17, s17, 7
	s_mul_i32 s17, s17, 1336
	s_add_u32 s18, s18, s17
	s_lshl_b32 s18, s18, 2
.Lcv_next_a:
	s_mov_b32 s41, 0
	s_cmp_ge_u32 s18, 22528
	s_cbranch_scc1 .Lcv_t1_2
	s_mul_hi_u32 s4, s18, 1525202
	s_mul_i32 s5, s4, 2816
	s_sub_u32 s17, s18, s5
	s_mul_hi_u32 s34, s17, 24403224
	s_mul_i32 s5, s34, 176
	s_sub_u32 s35, s17, s5
	s_lshl_b32 s40, s35, 5
	s_cmp_ge_u32 s40, 2816
	s_cselect_b32 s5, 1, 0
	s_mul_i32 s17, s5, 2816
	s_sub_u32 s40, s40, s17
	s_lshl_b32 s5, s5, 5
	s_lshr_b32 s17, s40, 6
	s_lshl_b32 s17, s17, 7
	s_add_u32 s5, s5, s17
	s_bfe_u32 s17, s40, 0x10005
	s_lshl_b32 s17, s17, 6
	s_add_u32 s40, s5, s17
	v_readlane_b32 s8, v237, 29
	v_readlane_b32 s9, v237, 30
	s_mul_i32 s5, s4, 0x1600000
	s_mul_i32 s17, s34, 0x160000
	s_add_u32 s5, s5, s17
	s_lshl_b32 s17, s35, 7
	s_add_u32 s5, s5, s17
	s_add_u32 s8, s8, s5
	s_addc_u32 s9, s9, 0
	s_movk_i32 s16, 0x5800
	v_readlane_b32 s14, v235, 34
	v_readlane_b32 s15, v235, 35
	s_mul_i32 s5, s4, 0xbb0000
	s_mul_i32 s17, s40, 0x880
	s_add_u32 s5, s5, s17
	s_lshl_b32 s17, s34, 7
	s_add_u32 s5, s5, s17
	s_add_u32 s5, s5, 0x8000
	s_add_u32 s14, s14, s5
	s_addc_u32 s15, s15, 0
	s_lshl_b32 s41, s41, 31
	s_or_b32 s13, s41, 0x880
	s_branch .Lcv_dec2
.Lcv_t1_2:
	s_cmp_ge_u32 s18, 33792
	s_cbranch_scc1 .Lcv_t2_2
	s_sub_u32 s17, s18, 22528
	s_mul_hi_u32 s4, s17, 3050403
	s_mul_i32 s5, s4, 1408
	s_sub_u32 s17, s17, s5
	s_lshr_b32 s34, s17, 5
	s_and_b32 s35, s17, 31
	s_lshl_b32 s40, s35, 5
	v_readlane_b32 s8, v237, 31
	v_readlane_b32 s9, v237, 32
	s_mul_i32 s5, s4, 0xb00000
	s_mul_i32 s17, s34, 0x40000
	s_add_u32 s5, s5, s17
	s_lshl_b32 s17, s35, 7
	s_add_u32 s5, s5, s17
	s_add_u32 s8, s8, s5
	s_addc_u32 s9, s9, 0
	s_movk_i32 s16, 0x1000
	v_readlane_b32 s14, v235, 34
	v_readlane_b32 s15, v235, 35
	s_mul_i32 s5, s4, 0x5a0000
	s_mul_i32 s17, s40, 0x1680
	s_add_u32 s5, s5, s17
	s_lshl_b32 s17, s34, 7
	s_add_u32 s5, s5, s17
	s_add_u32 s5, s5, 0x5d88000
	s_add_u32 s14, s14, s5
	s_addc_u32 s15, s15, 0
	s_lshl_b32 s41, s41, 31
	s_or_b32 s13, s41, 0x1680
	s_branch .Lcv_dec2
.Lcv_t2_2:
	s_cmp_ge_u32 s18, 40704
	s_cbranch_scc1 .Lcv_t3_2
	s_sub_u32 s17, s18, 33792
	s_mul_hi_u32 s4, s17, 2485514
	s_mul_i32 s5, s4, 1728
	s_sub_u32 s17, s17, s5
	s_mul_hi_u32 s34, s17, 39768216
	s_mul_i32 s5, s34, 108
	s_sub_u32 s35, s17, s5
	s_lshl_b32 s40, s35, 5
	s_cmp_ge_u32 s35, 105
	s_cselect_b32 s41, 1, 0
	s_cselect_b32 s35, 104, s35
	v_readlane_b32 s8, v237, 33
	v_readlane_b32 s9, v237, 34
	s_mul_i32 s5, s4, 0xd20000
	s_mul_i32 s17, s34, 0xd2000
	s_add_u32 s5, s5, s17
	s_lshl_b32 s17, s35, 7
	s_add_u32 s5, s5, s17
	s_add_u32 s8, s8, s5
	s_addc_u32 s9, s9, 0
	s_movk_i32 s16, 0x3480
	v_readlane_b32 s14, v235, 34
	v_readlane_b32 s15, v235, 35
	s_mul_i32 s5, s4, 0x72c000
	s_mul_i32 s17, s40, 0x880
	s_add_u32 s5, s5, s17
	s_lshl_b32 s17, s34, 7
	s_add_u32 s5, s5, s17
	s_add_u32 s5, s5, 0x8a88000
	s_add_u32 s14, s14, s5
	s_addc_u32 s15, s15, 0
	s_lshl_b32 s41, s41, 31
	s_or_b32 s13, s41, 0x880
	s_branch .Lcv_dec2
.Lcv_t3_2:
	s_sub_u32 s17, s18, 40704
	s_lshr_b32 s4, s17, 9
	s_and_b32 s17, s17, 511
	s_lshr_b32 s34, s17, 5
	s_and_b32 s35, s17, 31
	s_lshl_b32 s40, s35, 5
	v_readlane_b32 s8, v237, 35
	v_readlane_b32 s9, v237, 36
	s_mul_i32 s5, s4, 0x400000
	s_mul_i32 s17, s34, 0x40000
	s_add_u32 s5, s5, s17
	s_lshl_b32 s17, s35, 7
	s_add_u32 s5, s5, s17
	s_add_u32 s8, s8, s5
	s_addc_u32 s9, s9, 0
	s_movk_i32 s16, 0x1000
	v_readlane_b32 s14, v235, 34
	v_readlane_b32 s15, v235, 35
	s_mul_i32 s5, s4, 0x220000
	s_mul_i32 s17, s40, 0x880
	s_add_u32 s5, s5, s17
	s_lshl_b32 s17, s34, 7
	s_add_u32 s5, s5, s17
	s_add_u32 s5, s5, 0xa738000
	s_add_u32 s14, s14, s5
	s_addc_u32 s15, s15, 0
	s_lshl_b32 s41, s41, 31
	s_or_b32 s13, s41, 0x880
	s_branch .Lcv_dec2
.Lcv_dec2:
	v_mad_u32_u24 v100, v96, s16, v97
	global_load_dwordx4 v[32:35], v100, s[8:9]
	s_add_u32 s8, s8, s16
	s_addc_u32 s9, s9, 0
	global_load_dwordx4 v[36:39], v100, s[8:9]
	s_add_u32 s8, s8, s16
	s_addc_u32 s9, s9, 0
	global_load_dwordx4 v[40:43], v100, s[8:9]
	s_add_u32 s8, s8, s16
	s_addc_u32 s9, s9, 0
	global_load_dwordx4 v[44:47], v100, s[8:9]
	s_add_u32 s8, s8, s16
	s_addc_u32 s9, s9, 0
	global_load_dwordx4 v[48:51], v100, s[8:9]
	s_add_u32 s8, s8, s16
	s_addc_u32 s9, s9, 0
	global_load_dwordx4 v[52:55], v100, s[8:9]
	s_add_u32 s8, s8, s16
	s_addc_u32 s9, s9, 0
	global_load_dwordx4 v[56:59], v100, s[8:9]
	s_add_u32 s8, s8, s16
	s_addc_u32 s9, s9, 0
	global_load_dwordx4 v[60:63], v100, s[8:9]
	s_and_b32 s17, s6, 3
	s_cmp_lg_u32 s17, 0
	s_cbranch_scc1 .Lcv_w12_a
	s_cmp_eq_u32 s19, 1
	s_cbranch_scc1 .Lcv_w9_a
	s_waitcnt vmcnt(13)
	s_branch .Lcv_go_a
.Lcv_w9_a:
	s_waitcnt vmcnt(9)
	s_branch .Lcv_go_a
.Lcv_w12_a:
	s_waitcnt vmcnt(12)
	s_branch .Lcv_go_a
.Lcv_nonext_a:
	s_mov_b32 s18, 0xffffffff
	s_waitcnt vmcnt(0)
.Lcv_go_a:
	s_mov_b32 s19, 0
	v_cvt_pk_bf16_f32 v64, v0, v4
	v_cvt_pk_bf16_f32 v65, v8, v12
	v_cvt_pk_bf16_f32 v66, v16, v20
	v_cvt_pk_bf16_f32 v67, v24, v28
	v_cvt_pk_bf16_f32 v68, v1, v5
	v_cvt_pk_bf16_f32 v69, v9, v13
	v_cvt_pk_bf16_f32 v70, v17, v21
	v_cvt_pk_bf16_f32 v71, v25, v29
	v_cvt_pk_bf16_f32 v72, v2, v6
	v_cvt_pk_bf16_f32 v73, v10, v14
	v_cvt_pk_bf16_f32 v74, v18, v22
	v_cvt_pk_bf16_f32 v75, v26, v30
	v_cvt_pk_bf16_f32 v76, v3, v7
	v_cvt_pk_bf16_f32 v77, v11, v15
	v_cvt_pk_bf16_f32 v78, v19, v23
	v_cvt_pk_bf16_f32 v79, v27, v31
	s_bitcmp1_b32 s12, 31
	s_cbranch_scc0 .Lcv_nz_a
	v_mov_b32_e32 v64, 0
	v_mov_b32_e32 v65, 0
	v_mov_b32_e32 v66, 0
	v_mov_b32_e32 v67, 0
	v_mov_b32_e32 v68, 0
	v_mov_b32_e32 v69, 0
	v_mov_b32_e32 v70, 0
	v_mov_b32_e32 v71, 0
	v_mov_b32_e32 v72, 0
	v_mov_b32_e32 v73, 0
	v_mov_b32_e32 v74, 0
	v_mov_b32_e32 v75, 0
	v_mov_b32_e32 v76, 0
	v_mov_b32_e32 v77, 0
	v_mov_b32_e32 v78, 0
	v_mov_b32_e32 v79, 0
.Lcv_nz_a:
	s_and_b32 s12, s12, 0x7fffffff
	v_mad_u32_u24 v101, v98, s12, v99
	global_store_dwordx4 v101, v[64:67], s[10:11]
	s_add_u32 s10, s10, s12
	s_addc_u32 s11, s11, 0
	global_store_dwordx4 v101, v[68:71], s[10:11]
	s_add_u32 s10, s10, s12
	s_addc_u32 s11, s11, 0
	global_store_dwordx4 v101, v[72:75], s[10:11]
	s_add_u32 s10, s10, s12
	s_addc_u32 s11, s11, 0
	global_store_dwordx4 v101, v[76:79], s[10:11]
	s_cmp_eq_u32 s18, 0xffffffff
	s_cbranch_scc1 .Lcv_done
	s_mov_b32 s6, s18
	s_and_b32 s18, s6, 3
	s_cmp_lg_u32 s18, 0
	s_cbranch_scc1 .Lcv_noask_b
	v_readlane_b32 s4, v235, 34
	v_readlane_b32 s5, v235, 35
	s_mov_b64 s[34:35], exec
	s_mov_b64 exec, 1
	v_readlane_b32 s17, v237, 0
	s_and_b32 s17, s17, 7
	s_lshl_b32 s17, s17, 8
	s_add_u32 s17, s17, 0x40e0
	v_mov_b32_e32 v104, s17
	v_mov_b32_e32 v105, 1
	s_nop 1
	global_atomic_add v103, v104, v105, s[4:5] sc0
	s_mov_b64 exec, s[34:35]

.Lcv_next_b:
	s_mov_b32 s41, 0
	s_cmp_ge_u32 s18, 22528
	s_cbranch_scc1 .Lcv_t1_3
	s_mul_hi_u32 s4, s18, 1525202
	s_mul_i32 s5, s4, 2816
	s_sub_u32 s17, s18, s5
	s_mul_hi_u32 s34, s17, 24403224
	s_mul_i32 s5, s34, 176
	s_sub_u32 s35, s17, s5
	s_lshl_b32 s40, s35, 5
	s_cmp_ge_u32 s40, 2816
	s_cselect_b32 s5, 1, 0
	s_mul_i32 s17, s5, 2816
	s_sub_u32 s40, s40, s17
	s_lshl_b32 s5, s5, 5
	s_lshr_b32 s17, s40, 6
	s_lshl_b32 s17, s17, 7
	s_add_u32 s5, s5, s17
	s_bfe_u32 s17, s40, 0x10005
	s_lshl_b32 s17, s17, 6
	s_add_u32 s40, s5, s17
	v_readlane_b32 s8, v237, 29
	v_readlane_b32 s9, v237, 30
	s_mul_i32 s5, s4, 0x1600000
	s_mul_i32 s17, s34, 0x160000
	s_add_u32 s5, s5, s17
	s_lshl_b32 s17, s35, 7
	s_add_u32 s5, s5, s17
	s_add_u32 s8, s8, s5
	s_addc_u32 s9, s9, 0
	s_movk_i32 s16, 0x5800
	v_readlane_b32 s10, v235, 34
	v_readlane_b32 s11, v235, 35
	s_mul_i32 s5, s4, 0xbb0000
	s_mul_i32 s17, s40, 0x880
	s_add_u32 s5, s5, s17
	s_lshl_b32 s17, s34, 7
	s_add_u32 s5, s5, s17
	s_add_u32 s5, s5, 0x8000
	s_add_u32 s10, s10, s5
	s_addc_u32 s11, s11, 0
	s_lshl_b32 s41, s41, 31
	s_or_b32 s12, s41, 0x880
	s_branch .Lcv_dec3
.Lcv_t1_3:
	s_cmp_ge_u32 s18, 33792
	s_cbranch_scc1 .Lcv_t2_3
	s_sub_u32 s17, s18, 22528
	s_mul_hi_u32 s4, s17, 3050403
	s_mul_i32 s5, s4, 1408
	s_sub_u32 s17, s17, s5
	s_lshr_b32 s34, s17, 5
	s_and_b32 s35, s17, 31
	s_lshl_b32 s40, s35, 5
	v_readlane_b32 s8, v237, 31
	v_readlane_b32 s9, v237, 32
	s_mul_i32 s5, s4, 0xb00000
	s_mul_i32 s17, s34, 0x40000
	s_add_u32 s5, s5, s17
	s_lshl_b32 s17, s35, 7
	s_add_u32 s5, s5, s17
	s_add_u32 s8, s8, s5
	s_addc_u32 s9, s9, 0
	s_movk_i32 s16, 0x1000
	v_readlane_b32 s10, v235, 34
	v_readlane_b32 s11, v235, 35
	s_mul_i32 s5, s4, 0x5a0000
	s_mul_i32 s17, s40, 0x1680
	s_add_u32 s5, s5, s17
	s_lshl_b32 s17, s34, 7
	s_add_u32 s5, s5, s17
	s_add_u32 s5, s5, 0x5d88000
	s_add_u32 s10, s10, s5
	s_addc_u32 s11, s11, 0
	s_lshl_b32 s41, s41, 31
	s_or_b32 s12, s41, 0x1680
	s_branch .Lcv_dec3
.Lcv_t2_3:
	s_cmp_ge_u32 s18, 40704
	s_cbranch_scc1 .Lcv_t3_3
	s_sub_u32 s17, s18, 33792
	s_mul_hi_u32 s4, s17, 2485514
	s_mul_i32 s5, s4, 1728
	s_sub_u32 s17, s17, s5
	s_mul_hi_u32 s34, s17, 39768216
	s_mul_i32 s5, s34, 108
	s_sub_u32 s35, s17, s5
	s_lshl_b32 s40, s35, 5
	s_cmp_ge_u32 s35, 105
	s_cselect_b32 s41, 1, 0
	s_cselect_b32 s35, 104, s35
	v_readlane_b32 s8, v237, 33
	v_readlane_b32 s9, v237, 34
	s_mul_i32 s5, s4, 0xd20000
	s_mul_i32 s17, s34, 0xd2000
	s_add_u32 s5, s5, s17
	s_lshl_b32 s17, s35, 7
	s_add_u32 s5, s5, s17
	s_add_u32 s8, s8, s5
	s_addc_u32 s9, s9, 0
	s_movk_i32 s16, 0x3480
	v_readlane_b32 s10, v235, 34
	v_readlane_b32 s11, v235, 35
	s_mul_i32 s5, s4, 0x72c000
	s_mul_i32 s17, s40, 0x880
	s_add_u32 s5, s5, s17
	s_lshl_b32 s17, s34, 7
	s_add_u32 s5, s5, s17
	s_add_u32 s5, s5, 0x8a88000
	s_add_u32 s10, s10, s5
	s_addc_u32 s11, s11, 0
	s_lshl_b32 s41, s41, 31
	s_or_b32 s12, s41, 0x880
	s_branch .Lcv_dec3
.Lcv_t3_3:
	s_sub_u32 s17, s18, 40704
	s_lshr_b32 s4, s17, 9
	s_and_b32 s17, s17, 511
	s_lshr_b32 s34, s17, 5
	s_and_b32 s35, s17, 31
	s_lshl_b32 s40, s35, 5
	v_readlane_b32 s8, v237, 35
	v_readlane_b32 s9, v237, 36
	s_mul_i32 s5, s4, 0x400000
	s_mul_i32 s17, s34, 0x40000
	s_add_u32 s5, s5, s17
	s_lshl_b32 s17, s35, 7
	s_add_u32 s5, s5, s17
	s_add_u32 s8, s8, s5
	s_addc_u32 s9, s9, 0
	s_movk_i32 s16, 0x1000
	v_readlane_b32 s10, v235, 34
	v_readlane_b32 s11, v235, 35
	s_mul_i32 s5, s4, 0x220000
	s_mul_i32 s17, s40, 0x880
	s_add_u32 s5, s5, s17
	s_lshl_b32 s17, s34, 7
	s_add_u32 s5, s5, s17
	s_add_u32 s5, s5, 0xa738000
	s_add_u32 s10, s10, s5
	s_addc_u32 s11, s11, 0
	s_lshl_b32 s41, s41, 31
	s_or_b32 s12, s41, 0x880
	s_branch .Lcv_dec3
.Lcv_dec3:
	v_mad_u32_u24 v100, v96, s16, v97
	global_load_dwordx4 v[0:3], v100, s[8:9]
	s_add_u32 s8, s8, s16
	s_addc_u32 s9, s9, 0
	global_load_dwordx4 v[4:7], v100, s[8:9]
	s_add_u32 s8, s8, s16
	s_addc_u32 s9, s9, 0
	global_load_dwordx4 v[8:11], v100, s[8:9]
	s_add_u32 s8, s8, s16
	s_addc_u32 s9, s9, 0
	global_load_dwordx4 v[12:15], v100, s[8:9]
	s_add_u32 s8, s8, s16
	s_addc_u32 s9, s9, 0
	global_load_dwordx4 v[16:19], v100, s[8:9]
	s_add_u32 s8, s8, s16
	s_addc_u32 s9, s9, 0
	global_load_dwordx4 v[20:23], v100, s[8:9]
	s_add_u32 s8, s8, s16
	s_addc_u32 s9, s9, 0
	global_load_dwordx4 v[24:27], v100, s[8:9]
	s_add_u32 s8, s8, s16
	s_addc_u32 s9, s9, 0
	global_load_dwordx4 v[28:31], v100, s[8:9]
	s_and_b32 s17, s6, 3
	s_cmp_lg_u32 s17, 0
	s_cbranch_scc1 .Lcv_w12_b
	s_cmp_eq_u32 s19, 1
	s_cbranch_scc1 .Lcv_w9_b
	s_waitcnt vmcnt(13)
	s_branch .Lcv_go_b

.Lcv_go_b:
	s_mov_b32 s19, 0
	v_cvt_pk_bf16_f32 v64, v32, v36
	v_cvt_pk_bf16_f32 v65, v40, v44
	v_cvt_pk_bf16_f32 v66, v48, v52
	v_cvt_pk_bf16_f32 v67, v56, v60
	v_cvt_pk_bf16_f32 v68, v33, v37
	v_cvt_pk_bf16_f32 v69, v41, v45
	v_cvt_pk_bf16_f32 v70, v49, v53
	v_cvt_pk_bf16_f32 v71, v57, v61
	v_cvt_pk_bf16_f32 v72, v34, v38
	v_cvt_pk_bf16_f32 v73, v42, v46
	v_cvt_pk_bf16_f32 v74, v50, v54
	v_cvt_pk_bf16_f32 v75, v58, v62
	v_cvt_pk_bf16_f32 v76, v35, v39
	v_cvt_pk_bf16_f32 v77, v43, v47
	v_cvt_pk_bf16_f32 v78, v51, v55
	v_cvt_pk_bf16_f32 v79, v59, v63
	s_bitcmp1_b32 s13, 31
	s_cbranch_scc0 .Lcv_nz_b
	v_mov_b32_e32 v64, 0
	v_mov_b32_e32 v65, 0
	v_mov_b32_e32 v66, 0
	v_mov_b32_e32 v67, 0
	v_mov_b32_e32 v68, 0
	v_mov_b32_e32 v69, 0
	v_mov_b32_e32 v70, 0
	v_mov_b32_e32 v71, 0
	v_mov_b32_e32 v72, 0
	v_mov_b32_e32 v73, 0
	v_mov_b32_e32 v74, 0
	v_mov_b32_e32 v75, 0
	v_mov_b32_e32 v76, 0
	v_mov_b32_e32 v77, 0
	v_mov_b32_e32 v78, 0
	v_mov_b32_e32 v79, 0
.Lcv_nz_b:
	s_and_b32 s13, s13, 0x7fffffff
	v_mad_u32_u24 v101, v98, s13, v99
	global_store_dwordx4 v101, v[64:67], s[14:15]
	s_add_u32 s14, s14, s13
	s_addc_u32 s15, s15, 0
	global_store_dwordx4 v101, v[68:71], s[14:15]
	s_add_u32 s14, s14, s13
	s_addc_u32 s15, s15, 0
	global_store_dwordx4 v101, v[72:75], s[14:15]
	s_add_u32 s14, s14, s13
	s_addc_u32 s15, s15, 0
	global_store_dwordx4 v101, v[76:79], s[14:15]
	s_cmp_eq_u32 s18, 0xffffffff
	s_cbranch_scc1 .Lcv_done
	s_mov_b32 s6, s18
	s_branch .Lcv_loop
.Lcv_done:
.LBB0_1375:
	s_add_i32 s60, s60, 1
	s_cmp_ge_i32 s60, s61
	s_cselect_b64 s[34:35], -1, 0
	s_cmp_lt_i32 s60, s61
	v_readlane_b32 s40, v237, 1
	s_cselect_b64 s[36:37], -1, 0
	v_readlane_b32 s41, v237, 2
	s_and_b64 s[36:37], s[40:41], s[36:37]
	v_readlane_b32 s62, v235, 25
	v_readlane_b32 s74, v235, 27
	v_readlane_b32 s88, v235, 29
	v_readlane_b32 s90, v235, 31
	s_andn2_b64 vcc, exec, s[36:37]
	v_readlane_b32 s63, v235, 26
	v_readlane_b32 s75, v235, 28
	v_readlane_b32 s89, v235, 30
	v_readlane_b32 s91, v235, 32
	s_cbranch_vccz .LBB0_1376
	s_getpc_b64 s[98:99]
